# v28 + P7 lane-group sum via v_permlane32/16_swap packed reduction instead of 16 ds_bpermute; carry state held per 16-lane row (2 regs, 4 FMAs, 2 full-wave stores)
# speedup vs baseline: 1.0135x; 1.0135x over previous
; template <int DIR>
; __device__ __forceinline__ void s5_local_dir(const bf16_t* UZ, unsigned char* ws, int gw, int NGW, int lane) {
;     float* E = (float*)(ws + WS_E);
;     const int pair = gw & 127, g = pair & 63, fr = lane & 15, fq = lane >> 4;
;     const bf16_t* Bb = (const bf16_t*)(ws + WS_BB) + (size_t)pair * 128 * 16;
;     bf16x4 Bre[4][4], Bim[4][4]; float a1r[4], a1i[4], a64r[4], a64i[4], wr_[4], wi_[4];
; #pragma unroll
;     for (int t = 0; t < 4; ++t) {
;         const int p = 16 * t + fr;
;         const bf16x4 b_re = *(const bf16x4*)(Bb + (2 * p) * 16 + 4 * fq), b_im = *(const bf16x4*)(Bb + (2 * p + 1) * 16 + 4 * fq);
;         const f32x4 ap = ((const f32x4*)(ws + WS_APOW))[pair * 64 + p];
;         const float ar = ap.x, ai = ap.y;
;         float r2 = ar, i2 = ai; cmul(r2, i2, ar, ai);
;         float r4 = r2, i4 = i2; cmul(r4, i4, r2, i2);
;         float r8 = r4, i8 = i4; cmul(r8, i8, r4, i4);
;         float r12 = r8, i12 = i8; cmul(r12, i12, r4, i4);
;         float r16 = r8, i16 = i8; cmul(r16, i16, r8, i8);
;         float r32 = r16, i32 = i16; cmul(r32, i32, r16, i16);
;         float r48 = r32, i48 = i32; cmul(r48, i48, r16, i16);
;         a1r[t] = ar; a1i[t] = ai; a64r[t] = ap.z; a64i[t] = ap.w;
;         const int e = DIR ? fq : 3 - fq;
;         wr_[t] = e == 0 ? 1.f : e == 1 ? r4 : e == 2 ? r8 : r12; wi_[t] = e == 0 ? 0.f : e == 1 ? i4 : e == 2 ? i8 : i12;
; #pragma unroll
;         for (int m = 0; m < 4; ++m) {
;             const int em = DIR ? m : 3 - m;
;             const float pr = em == 0 ? 1.f : em == 1 ? r16 : em == 2 ? r32 : r48, pi = em == 0 ? 0.f : em == 1 ? i16 : em == 2 ? i32 : i48;
;             Bre[m][t] = cscale_bf(b_re, b_im, pr, pi, false); Bim[m][t] = cscale_bf(b_re, b_im, pr, pi, true);
;         }
;     }
;     const int qd = gw >> 7, b = qd >> 2, q = qd & 3;
;     if (qd >= 16) return;
;     const int c0 = 17 * q, c1 = q < 3 ? c0 + 17 : 67;
;     float Rr[4] = {0.f, 0.f, 0.f, 0.f}, Ri[4] = {0.f, 0.f, 0.f, 0.f};
; __device__ __forceinline__ void s5_local_phase(LAS unsigned char* lds, const bf16_t* UZ, unsigned char* ws) {
;     const int lane = threadIdx.x & 63, wave = __builtin_amdgcn_readfirstlane(threadIdx.x >> 6);
;     const int gw = blockIdx.x * 8 + wave, NGW = gridDim.x * 8;
;     if ((gw & 127) >> 6) s5_local_dir<1>(UZ, ws, gw, NGW, lane); else s5_local_dir<0>(UZ, ws, gw, NGW, lane);
.LBB0_644:
	s_cmp_lt_i32 s68, 8
	s_cselect_b64 s[0:1], -1, 0
	s_and_b64 s[0:1], s[0:1], s[2:3]
	s_andn2_b64 vcc, exec, s[0:1]
	s_cbranch_vccnz .LBB0_690
	v_readfirstlane_b32 s2, v192
	s_lshr_b32 s40, s2, 6
	s_lshl_b32 s2, s12, 3
	s_add_i32 s40, s40, s2
	s_and_b32 s2, s40, 64
	s_add_u32 s41, s30, 0x100000
	s_addc_u32 s42, s31, 0
	s_add_u32 s4, s30, 0x80000
	s_addc_u32 s5, s31, 0
	v_and_b32_e32 v127, 15, v192
	v_bfe_u32 v128, v192, 4, 2
	v_and_b32_e32 v126, 63, v192
	s_cmp_eq_u32 s2, 0
	v_lshlrev_b32_e32 v129, 2, v128
	v_lshlrev_b32_e32 v130, 5, v127
	s_cbranch_scc1 .LBB0_662
	s_ashr_i32 s2, s40, 7
	s_cmp_lt_i32 s2, 16
	s_mov_b64 s[22:23], 0
	s_cbranch_scc0 .LBB0_663
	s_and_b32 s43, s2, 3
	s_mul_i32 s38, s43, 17
	s_ashr_i32 s36, s40, 9
	s_and_b32 s44, s40, 63
	s_add_i32 s37, s38, 17
	s_cmp_lg_u32 s43, 3
	s_cselect_b64 s[24:25], -1, 0
	s_and_b64 s[2:3], s[24:25], exec
	s_cselect_b32 s46, s37, 0x43
	s_lshl_b32 s45, s36, 7
	v_cmp_gt_u32_e64 s[8:9], 16, v126
	v_mov_b32_e32 v115, 0
	v_mov_b32_e32 v240, 0
	v_mov_b32_e32 v241, 0
	s_cmp_ge_u32 s38, s46
	v_mov_b32_e32 v114, 0
	v_mov_b32_e32 v112, 0
	v_mov_b32_e32 v110, 0
	v_mov_b32_e32 v113, 0
	v_mov_b32_e32 v111, 0
	v_mov_b32_e32 v109, 0
	v_mov_b32_e32 v108, 0
	s_cbranch_scc1 .LBB0_684
	s_and_b32 s37, s40, 0x7f
	s_lshl_b32 s2, s37, 12
	s_add_u32 s2, s41, s2
	s_addc_u32 s3, s42, 0
	s_lshl_b32 s37, s37, 6
	s_waitcnt vmcnt(0)
	v_or_b32_e32 v0, s37, v127
	v_lshlrev_b32_e32 v0, 4, v0
	global_load_dwordx4 v[0:3], v0, s[4:5]
	v_lshlrev_b32_e32 v16, 1, v130
	v_mov_b32_e32 v17, 0
	v_lshl_add_u64 v[4:5], s[2:3], 0, v[16:17]
	v_lshlrev_b32_e32 v16, 1, v129
	v_lshl_add_u64 v[4:5], v[4:5], 0, v[16:17]
	global_load_dwordx2 v[22:23], v[4:5], off
	global_load_dwordx2 v[26:27], v[4:5], off offset:32
	v_or_b32_e32 v10, 16, v127
	v_or_b32_e32 v11, 32, v127
	v_or_b32_e32 v12, 48, v126
	v_lshlrev_b32_e32 v4, 6, v10
	v_mov_b32_e32 v5, v17
	v_lshlrev_b32_e32 v6, 6, v11
	v_mov_b32_e32 v7, v17
	v_lshlrev_b32_e32 v8, 6, v12
	v_mov_b32_e32 v9, v17
	v_lshl_add_u64 v[4:5], s[2:3], 0, v[4:5]
	v_lshrrev_b32_e32 v13, 1, v192
	v_or_b32_e32 v10, s37, v10
	v_lshl_add_u64 v[6:7], s[2:3], 0, v[6:7]
	v_or_b32_e32 v11, s37, v11
	v_lshl_add_u64 v[8:9], s[2:3], 0, v[8:9]
	v_or_b32_e32 v12, s37, v12
	v_lshl_add_u64 v[18:19], v[4:5], 0, v[16:17]
	v_lshlrev_b32_e32 v28, 4, v10
	v_lshl_add_u64 v[20:21], v[6:7], 0, v[16:17]
	v_lshlrev_b32_e32 v29, 4, v11
	v_lshl_add_u64 v[24:25], v[8:9], 0, v[16:17]
	v_lshlrev_b32_e32 v30, 4, v12
	v_and_b32_e32 v16, 24, v13
	global_load_dwordx2 v[50:51], v[18:19], off
	global_load_dwordx2 v[48:49], v[18:19], off offset:32
	global_load_dwordx4 v[4:7], v28, s[4:5]
	global_load_dwordx2 v[72:73], v[20:21], off
	global_load_dwordx2 v[70:71], v[20:21], off offset:32
	global_load_dwordx4 v[8:11], v29, s[4:5]
	global_load_dwordx2 v[94:95], v[24:25], off
	global_load_dwordx2 v[92:93], v[24:25], off offset:32
	global_load_dwordx4 v[12:15], v30, s[4:5]
	s_lshl_b32 s39, s44, 5
	s_add_u32 s2, s18, s39
	s_addc_u32 s3, s19, 0
	v_cmp_eq_u32_e32 vcc, 2, v128
	v_lshl_add_u64 v[18:19], s[2:3], 0, v[16:17]
	v_cmp_eq_u32_e64 s[2:3], 1, v128
	s_mov_b32 s37, 0x5040100
	s_lshl_b32 s47, s36, 8
	s_lshl_b32 s48, s36, 12
	s_addk_i32 s47, 0x40c0
	s_addk_i32 s48, 0x10c0
	s_cmp_eq_u32 s43, 0
	s_waitcnt vmcnt(11)
	v_pk_mul_f32 v[24:25], v[0:1], v[0:1] op_sel:[1,1] op_sel_hi:[1,0]
	s_nop 0
	v_pk_fma_f32 v[28:29], v[0:1], v[0:1], v[24:25] op_sel_hi:[1,0,1] neg_lo:[0,0,1] neg_hi:[0,0,1]
	v_pk_fma_f32 v[24:25], v[0:1], v[0:1], v[24:25] op_sel_hi:[1,0,1]
	v_mov_b32_e32 v30, v28
	v_pk_mov_b32 v[32:33], v[24:25], v[28:29] op_sel:[1,0]
	v_mov_b32_e32 v31, v25
	v_pk_mul_f32 v[24:25], v[24:25], v[32:33] op_sel:[1,0]
	v_mov_b32_e32 v20, v0
	v_pk_fma_f32 v[32:33], v[28:29], v[30:31], v[24:25] op_sel_hi:[0,1,1] neg_lo:[0,0,1] neg_hi:[0,0,1]
	v_pk_fma_f32 v[24:25], v[28:29], v[30:31], v[24:25] op_sel_hi:[0,1,1]
	v_pk_mov_b32 v[30:31], v[24:25], v[32:33] op_sel:[1,0]
	v_mov_b32_e32 v28, v32
	v_mov_b32_e32 v29, v25
	v_pk_mul_f32 v[30:31], v[24:25], v[30:31] op_sel:[1,0]
	v_mov_b32_e32 v21, v0
	v_pk_fma_f32 v[34:35], v[32:33], v[28:29], v[30:31] op_sel_hi:[0,1,1] neg_lo:[0,0,1] neg_hi:[0,0,1]
	v_pk_fma_f32 v[30:31], v[32:33], v[28:29], v[30:31] op_sel_hi:[0,1,1]
	v_pk_mov_b32 v[38:39], v[30:31], v[34:35] op_sel:[1,0]
	v_mov_b32_e32 v36, v34
	v_mov_b32_e32 v37, v31
	v_pk_mul_f32 v[38:39], v[30:31], v[38:39] op_sel:[1,0]
	v_mul_f32_e32 v0, v25, v34
	v_pk_mul_f32 v[28:29], v[28:29], v[36:37]
	v_pk_fma_f32 v[44:45], v[34:35], v[36:37], v[38:39] op_sel_hi:[0,1,1] neg_lo:[0,0,1] neg_hi:[0,0,1]
	v_pk_fma_f32 v[36:37], v[34:35], v[36:37], v[38:39] op_sel_hi:[0,1,1]
	v_fmac_f32_e32 v0, v32, v31
	v_pk_mov_b32 v[38:39], v[36:37], v[44:45] op_sel:[1,0]
	v_sub_f32_e32 v16, v28, v29
	v_mov_b32_e32 v28, v44
	v_mov_b32_e32 v29, v37
	v_cndmask_b32_e32 v0, v0, v31, vcc
	v_pk_mul_f32 v[30:31], v[36:37], v[38:39] op_sel:[1,0]
	v_cndmask_b32_e64 v0, v0, v25, s[2:3]
	v_pk_fma_f32 v[46:47], v[44:45], v[28:29], v[30:31] op_sel_hi:[0,1,1] neg_lo:[0,0,1] neg_hi:[0,0,1]
	v_pk_fma_f32 v[52:53], v[44:45], v[28:29], v[30:31] op_sel_hi:[0,1,1]
	s_waitcnt vmcnt(9)
; __device__ __forceinline__ unsigned pk2(float lo, float hi) { f32x2 v = {lo, hi}; nbf2 r = __builtin_convertvector(v, nbf2); return __builtin_bit_cast(unsigned, r); }
; __device__ __forceinline__ bf16x4 cscale_bf(const bf16x4 re, const bf16x4 im, float wr, float wi, bool want_im) {
;     bf16x4 o;
; #pragma unroll
;     for (int k = 0; k < 4; k += 2) {
;         const float r0 = __uint_as_float((unsigned)(unsigned short)re[k] << 16), r1 = __uint_as_float((unsigned)(unsigned short)re[k + 1] << 16);
;         const float i0 = __uint_as_float((unsigned)(unsigned short)im[k] << 16), i1 = __uint_as_float((unsigned)(unsigned short)im[k + 1] << 16);
;         const unsigned w = want_im ? pk2(wr * i0 + wi * r0, wr * i1 + wi * r1) : pk2(wr * r0 - wi * i0, wr * r1 - wi * i1);
;         o[k] = (short)(w & 0xffffu); o[k + 1] = (short)(w >> 16);
;     }
;     return o;
; }
; template <int DIR>
; __device__ __forceinline__ void s5_local_dir(const bf16_t* UZ, unsigned char* ws, int gw, int NGW, int lane) {
;     ...
;     for (int t = 0; t < 4; ++t) {
;         const int p = 16 * t + fr;
;         const bf16x4 b_re = *(const bf16x4*)(Bb + (2 * p) * 16 + 4 * fq), b_im = *(const bf16x4*)(Bb + (2 * p + 1) * 16 + 4 * fq);
;         const f32x4 ap = ((const f32x4*)(ws + WS_APOW))[pair * 64 + p];
;         const float ar = ap.x, ai = ap.y;
;         float r2 = ar, i2 = ai; cmul(r2, i2, ar, ai);
;         float r4 = r2, i4 = i2; cmul(r4, i4, r2, i2);
;         float r8 = r4, i8 = i4; cmul(r8, i8, r4, i4);
;         float r12 = r8, i12 = i8; cmul(r12, i12, r4, i4);
;         float r16 = r8, i16 = i8; cmul(r16, i16, r8, i8);
;         float r32 = r16, i32 = i16; cmul(r32, i32, r16, i16);
;         float r48 = r32, i48 = i32; cmul(r48, i48, r16, i16);
;         a1r[t] = ar; a1i[t] = ai; a64r[t] = ap.z; a64i[t] = ap.w;
;         const int e = DIR ? fq : 3 - fq;
;         wr_[t] = e == 0 ? 1.f : e == 1 ? r4 : e == 2 ? r8 : r12; wi_[t] = e == 0 ? 0.f : e == 1 ? i4 : e == 2 ? i8 : i12;
; #pragma unroll
;         for (int m = 0; m < 4; ++m) {
;             const int em = DIR ? m : 3 - m;
;             const float pr = em == 0 ? 1.f : em == 1 ? r16 : em == 2 ? r32 : r48, pi = em == 0 ? 0.f : em == 1 ? i16 : em == 2 ? i32 : i48;
;             Bre[m][t] = cscale_bf(b_re, b_im, pr, pi, false); Bim[m][t] = cscale_bf(b_re, b_im, pr, pi, true);
;         }
	v_and_b32_e32 v43, 0xffff0000, v26
	v_lshlrev_b32_e32 v42, 16, v26
	v_cndmask_b32_e32 v16, v16, v34, vcc
	v_cndmask_b32_e64 v25, v0, 0, s[8:9]
	v_mov_b32_e32 v30, v46
	v_mov_b32_e32 v31, v53
	v_mul_f32_e32 v0, v37, v53
	v_and_b32_e32 v61, 0xffff0000, v27
	v_lshlrev_b32_e32 v60, 16, v27
	v_and_b32_e32 v41, 0xffff0000, v22
	v_lshlrev_b32_e32 v40, 16, v22
	v_cndmask_b32_e64 v16, v16, v32, s[2:3]
	v_pk_fma_f32 v[54:55], v[28:29], v[30:31], v[0:1] op_sel_hi:[1,1,0] neg_lo:[0,0,1] neg_hi:[0,0,1]
	v_and_b32_e32 v59, 0xffff0000, v23
	v_lshlrev_b32_e32 v58, 16, v23
	v_xor_b32_e32 v27, 0x80000000, v61
	v_xor_b32_e32 v26, 0x80000000, v60
	v_xor_b32_e32 v29, 0x80000000, v43
	v_xor_b32_e32 v28, 0x80000000, v42
	v_cndmask_b32_e64 v22, v16, 1.0, s[8:9]
	v_mul_f32_e32 v16, v44, v53
	v_pk_fma_f32 v[26:27], v[26:27], 0, v[58:59] op_sel_hi:[1,0,1]
	v_pk_fma_f32 v[28:29], v[28:29], 0, v[40:41] op_sel_hi:[1,0,1]
	v_pk_fma_f32 v[56:57], v[38:39], v[30:31], v[16:17] op_sel_hi:[1,1,0]
	v_cvt_pk_bf16_f32 v0, v28, s0
	v_cvt_pk_bf16_f32 v16, v29, s0
	v_cvt_pk_bf16_f32 v23, v26, s0
	v_cvt_pk_bf16_f32 v24, v27, s0
	v_pk_fma_f32 v[28:29], v[58:59], 0, v[60:61] op_sel_hi:[1,0,1]
	v_pk_fma_f32 v[30:31], v[40:41], 0, v[42:43] op_sel_hi:[1,0,1]
	v_pk_mul_f32 v[32:33], v[36:37], v[60:61] op_sel:[1,0]
	v_perm_b32 v27, v24, v23, s37
	v_perm_b32 v26, v16, v0, s37
	v_cvt_pk_bf16_f32 v0, v30, s0
	v_cvt_pk_bf16_f32 v16, v31, s0
	v_cvt_pk_bf16_f32 v23, v28, s0
	v_cvt_pk_bf16_f32 v24, v29, s0
	v_pk_mul_f32 v[30:31], v[36:37], v[42:43] op_sel:[1,0]
	v_pk_fma_f32 v[32:33], v[44:45], v[58:59], v[32:33] op_sel_hi:[0,1,1] neg_lo:[0,0,1] neg_hi:[0,0,1]
	v_pk_mul_f32 v[34:35], v[36:37], v[58:59] op_sel:[1,0]
	v_perm_b32 v29, v24, v23, s37
	v_pk_fma_f32 v[30:31], v[44:45], v[40:41], v[30:31] op_sel_hi:[0,1,1] neg_lo:[0,0,1] neg_hi:[0,0,1]
	v_cvt_pk_bf16_f32 v23, v32, s0
	v_cvt_pk_bf16_f32 v24, v33, s0
	v_pk_mul_f32 v[32:33], v[36:37], v[40:41] op_sel:[1,0]
	v_pk_fma_f32 v[34:35], v[44:45], v[60:61], v[34:35] op_sel_hi:[0,1,1]
	v_pk_mul_f32 v[36:37], v[52:53], v[60:61] op_sel:[1,0]
	v_perm_b32 v28, v16, v0, s37
	v_cvt_pk_bf16_f32 v0, v30, s0
	v_cvt_pk_bf16_f32 v16, v31, s0
	v_perm_b32 v31, v24, v23, s37
	v_pk_fma_f32 v[32:33], v[44:45], v[42:43], v[32:33] op_sel_hi:[0,1,1]
	v_cvt_pk_bf16_f32 v23, v34, s0
	v_cvt_pk_bf16_f32 v24, v35, s0
	v_pk_mul_f32 v[34:35], v[52:53], v[42:43] op_sel:[1,0]
	v_pk_fma_f32 v[36:37], v[46:47], v[58:59], v[36:37] op_sel_hi:[0,1,1] neg_lo:[0,0,1] neg_hi:[0,0,1]
	v_pk_mul_f32 v[38:39], v[52:53], v[58:59] op_sel:[1,0]
	v_perm_b32 v30, v16, v0, s37
	v_cvt_pk_bf16_f32 v0, v32, s0
	v_cvt_pk_bf16_f32 v16, v33, s0
	v_perm_b32 v33, v24, v23, s37
	v_pk_fma_f32 v[34:35], v[46:47], v[40:41], v[34:35] op_sel_hi:[0,1,1] neg_lo:[0,0,1] neg_hi:[0,0,1]
	v_cvt_pk_bf16_f32 v23, v36, s0
	v_cvt_pk_bf16_f32 v24, v37, s0
	v_pk_mul_f32 v[36:37], v[52:53], v[40:41] op_sel:[1,0]
	v_pk_fma_f32 v[38:39], v[46:47], v[60:61], v[38:39] op_sel_hi:[0,1,1]
	v_pk_mul_f32 v[44:45], v[56:57], v[60:61] op_sel_hi:[0,1]
	v_perm_b32 v32, v16, v0, s37
	v_cvt_pk_bf16_f32 v0, v34, s0
	v_cvt_pk_bf16_f32 v16, v35, s0
	v_perm_b32 v35, v24, v23, s37
	v_pk_fma_f32 v[36:37], v[46:47], v[42:43], v[36:37] op_sel_hi:[0,1,1]
	v_cvt_pk_bf16_f32 v23, v38, s0
	v_cvt_pk_bf16_f32 v24, v39, s0
	v_pk_fma_f32 v[44:45], v[54:55], v[58:59], v[44:45] op_sel_hi:[0,1,1] neg_lo:[0,0,1] neg_hi:[0,0,1]
	v_perm_b32 v34, v16, v0, s37
	v_cvt_pk_bf16_f32 v16, v37, s0
	v_perm_b32 v37, v24, v23, s37
	v_pk_mul_f32 v[38:39], v[56:57], v[42:43] op_sel_hi:[0,1]
	v_cvt_pk_bf16_f32 v23, v44, s0
	v_cvt_pk_bf16_f32 v24, v45, s0
	v_pk_mul_f32 v[44:45], v[56:57], v[58:59] op_sel_hi:[0,1]
	v_cvt_pk_bf16_f32 v0, v36, s0
	v_pk_fma_f32 v[38:39], v[54:55], v[40:41], v[38:39] op_sel_hi:[0,1,1] neg_lo:[0,0,1] neg_hi:[0,0,1]
	v_pk_fma_f32 v[44:45], v[54:55], v[60:61], v[44:45] op_sel_hi:[0,1,1]
	v_perm_b32 v36, v16, v0, s37
	v_cvt_pk_bf16_f32 v16, v39, s0
	v_perm_b32 v39, v24, v23, s37
	v_cvt_pk_bf16_f32 v23, v44, s0
	v_cvt_pk_bf16_f32 v24, v45, s0
	s_waitcnt vmcnt(6)
	v_pk_mul_f32 v[44:45], v[4:5], v[4:5] op_sel:[1,1] op_sel_hi:[1,0]
	v_pk_mul_f32 v[40:41], v[56:57], v[40:41] op_sel_hi:[0,1]
	v_pk_fma_f32 v[46:47], v[4:5], v[4:5], v[44:45] op_sel_hi:[1,0,1] neg_lo:[0,0,1] neg_hi:[0,0,1]
	v_pk_fma_f32 v[44:45], v[4:5], v[4:5], v[44:45] op_sel_hi:[1,0,1]
	v_pk_fma_f32 v[40:41], v[54:55], v[42:43], v[40:41] op_sel_hi:[0,1,1]
	v_pk_mov_b32 v[54:55], v[44:45], v[46:47] op_sel:[1,0]
	v_mov_b32_e32 v52, v46
	v_mov_b32_e32 v53, v45
	v_pk_mul_f32 v[44:45], v[44:45], v[54:55] op_sel:[1,0]
	v_cvt_pk_bf16_f32 v0, v38, s0
	v_pk_fma_f32 v[54:55], v[46:47], v[52:53], v[44:45] op_sel_hi:[0,1,1] neg_lo:[0,0,1] neg_hi:[0,0,1]
	v_pk_fma_f32 v[44:45], v[46:47], v[52:53], v[44:45] op_sel_hi:[0,1,1]
	v_pk_mov_b32 v[52:53], v[44:45], v[54:55] op_sel:[1,0]
	v_mov_b32_e32 v46, v54
	v_mov_b32_e32 v47, v45
	v_pk_mul_f32 v[52:53], v[44:45], v[52:53] op_sel:[1,0]
	v_perm_b32 v38, v16, v0, s37
	v_pk_fma_f32 v[56:57], v[54:55], v[46:47], v[52:53] op_sel_hi:[0,1,1] neg_lo:[0,0,1] neg_hi:[0,0,1]
	v_pk_fma_f32 v[52:53], v[54:55], v[46:47], v[52:53] op_sel_hi:[0,1,1]
	v_pk_mov_b32 v[60:61], v[52:53], v[56:57] op_sel:[1,0]
	v_mov_b32_e32 v58, v56
	v_mov_b32_e32 v59, v53
	v_pk_mul_f32 v[60:61], v[52:53], v[60:61] op_sel:[1,0]
	v_cvt_pk_bf16_f32 v0, v40, s0
	v_pk_fma_f32 v[62:63], v[56:57], v[58:59], v[60:61] op_sel_hi:[0,1,1] neg_lo:[0,0,1] neg_hi:[0,0,1]
	v_pk_fma_f32 v[60:61], v[56:57], v[58:59], v[60:61] op_sel_hi:[0,1,1]
	v_pk_mov_b32 v[66:67], v[60:61], v[62:63] op_sel:[1,0]
	v_mov_b32_e32 v64, v62
	v_mov_b32_e32 v65, v61
	v_pk_mul_f32 v[68:69], v[60:61], v[66:67] op_sel:[1,0]
; __device__ __forceinline__ unsigned pk2(float lo, float hi) { f32x2 v = {lo, hi}; nbf2 r = __builtin_convertvector(v, nbf2); return __builtin_bit_cast(unsigned, r); }
; __device__ __forceinline__ bf16x4 cscale_bf(const bf16x4 re, const bf16x4 im, float wr, float wi, bool want_im) {
;     bf16x4 o;
; #pragma unroll
;     for (int k = 0; k < 4; k += 2) {
;         const float r0 = __uint_as_float((unsigned)(unsigned short)re[k] << 16), r1 = __uint_as_float((unsigned)(unsigned short)re[k + 1] << 16);
;         const float i0 = __uint_as_float((unsigned)(unsigned short)im[k] << 16), i1 = __uint_as_float((unsigned)(unsigned short)im[k + 1] << 16);
;         const unsigned w = want_im ? pk2(wr * i0 + wi * r0, wr * i1 + wi * r1) : pk2(wr * r0 - wi * i0, wr * r1 - wi * i1);
;         o[k] = (short)(w & 0xffffu); o[k + 1] = (short)(w >> 16);
;     }
;     return o;
; }
; template <int DIR>
; __device__ __forceinline__ void s5_local_dir(const bf16_t* UZ, unsigned char* ws, int gw, int NGW, int lane) {
;     ...
;     for (int t = 0; t < 4; ++t) {
;         const int p = 16 * t + fr;
;         const bf16x4 b_re = *(const bf16x4*)(Bb + (2 * p) * 16 + 4 * fq), b_im = *(const bf16x4*)(Bb + (2 * p + 1) * 16 + 4 * fq);
;         const f32x4 ap = ((const f32x4*)(ws + WS_APOW))[pair * 64 + p];
;         const float ar = ap.x, ai = ap.y;
;         float r2 = ar, i2 = ai; cmul(r2, i2, ar, ai);
;         float r4 = r2, i4 = i2; cmul(r4, i4, r2, i2);
;         float r8 = r4, i8 = i4; cmul(r8, i8, r4, i4);
;         float r12 = r8, i12 = i8; cmul(r12, i12, r4, i4);
;         float r16 = r8, i16 = i8; cmul(r16, i16, r8, i8);
;         float r32 = r16, i32 = i16; cmul(r32, i32, r16, i16);
;         float r48 = r32, i48 = i32; cmul(r48, i48, r16, i16);
;         a1r[t] = ar; a1i[t] = ai; a64r[t] = ap.z; a64i[t] = ap.w;
;         const int e = DIR ? fq : 3 - fq;
;         wr_[t] = e == 0 ? 1.f : e == 1 ? r4 : e == 2 ? r8 : r12; wi_[t] = e == 0 ? 0.f : e == 1 ? i4 : e == 2 ? i8 : i12;
; #pragma unroll
;         for (int m = 0; m < 4; ++m) {
;             const int em = DIR ? m : 3 - m;
;             const float pr = em == 0 ? 1.f : em == 1 ? r16 : em == 2 ? r32 : r48, pi = em == 0 ? 0.f : em == 1 ? i16 : em == 2 ? i32 : i48;
;             Bre[m][t] = cscale_bf(b_re, b_im, pr, pi, false); Bim[m][t] = cscale_bf(b_re, b_im, pr, pi, true);
;         }
	v_cvt_pk_bf16_f32 v16, v41, s0
	v_pk_fma_f32 v[74:75], v[62:63], v[64:65], v[68:69] op_sel_hi:[0,1,1] neg_lo:[0,0,1] neg_hi:[0,0,1]
	v_pk_fma_f32 v[68:69], v[62:63], v[64:65], v[68:69] op_sel_hi:[0,1,1]
	v_perm_b32 v40, v16, v0, s37
	v_mov_b32_e32 v76, v74
	v_mov_b32_e32 v77, v69
	v_mul_f32_e32 v0, v61, v69
	v_pk_fma_f32 v[64:65], v[64:65], v[76:77], v[0:1] op_sel_hi:[1,1,0] neg_lo:[0,0,1] neg_hi:[0,0,1]
	v_mul_f32_e32 v0, v62, v69
	v_pk_fma_f32 v[66:67], v[66:67], v[76:77], v[0:1] op_sel_hi:[1,1,0]
	v_mul_f32_e32 v0, v45, v56
	v_pk_mul_f32 v[46:47], v[46:47], v[58:59]
	v_mov_b32_e32 v42, v4
	v_mov_b32_e32 v43, v4
	v_fmac_f32_e32 v0, v54, v53
	v_sub_f32_e32 v4, v46, v47
	v_and_b32_e32 v79, 0xffff0000, v48
	v_lshlrev_b32_e32 v78, 16, v48
	v_and_b32_e32 v83, 0xffff0000, v49
	v_lshlrev_b32_e32 v82, 16, v49
	v_cndmask_b32_e32 v4, v4, v56, vcc
	v_cndmask_b32_e32 v0, v0, v53, vcc
	v_and_b32_e32 v77, 0xffff0000, v50
	v_lshlrev_b32_e32 v76, 16, v50
	v_and_b32_e32 v81, 0xffff0000, v51
	v_lshlrev_b32_e32 v80, 16, v51
	v_xor_b32_e32 v49, 0x80000000, v83
	v_xor_b32_e32 v48, 0x80000000, v82
	v_xor_b32_e32 v51, 0x80000000, v79
	v_xor_b32_e32 v50, 0x80000000, v78
	v_cndmask_b32_e64 v4, v4, v54, s[2:3]
	v_cndmask_b32_e64 v0, v0, v45, s[2:3]
	v_pk_fma_f32 v[48:49], v[48:49], 0, v[80:81] op_sel_hi:[1,0,1]
	v_pk_fma_f32 v[50:51], v[50:51], 0, v[76:77] op_sel_hi:[1,0,1]
	v_perm_b32 v41, v24, v23, s37
	v_cndmask_b32_e64 v44, v4, 1.0, s[8:9]
	v_cndmask_b32_e64 v47, v0, 0, s[8:9]
	v_cvt_pk_bf16_f32 v0, v50, s0
	v_cvt_pk_bf16_f32 v4, v51, s0
	v_cvt_pk_bf16_f32 v16, v48, s0
	v_cvt_pk_bf16_f32 v23, v49, s0
	v_pk_fma_f32 v[50:51], v[80:81], 0, v[82:83] op_sel_hi:[1,0,1]
	v_pk_fma_f32 v[52:53], v[76:77], 0, v[78:79] op_sel_hi:[1,0,1]
	v_pk_mul_f32 v[54:55], v[60:61], v[82:83] op_sel:[1,0]
	v_perm_b32 v49, v23, v16, s37
	v_perm_b32 v48, v4, v0, s37
	v_cvt_pk_bf16_f32 v0, v52, s0
	v_cvt_pk_bf16_f32 v4, v53, s0
	v_cvt_pk_bf16_f32 v16, v50, s0
	v_cvt_pk_bf16_f32 v23, v51, s0
	v_pk_mul_f32 v[52:53], v[60:61], v[78:79] op_sel:[1,0]
	v_pk_fma_f32 v[54:55], v[62:63], v[80:81], v[54:55] op_sel_hi:[0,1,1] neg_lo:[0,0,1] neg_hi:[0,0,1]
	v_pk_mul_f32 v[56:57], v[60:61], v[80:81] op_sel:[1,0]
	v_perm_b32 v51, v23, v16, s37
	v_pk_fma_f32 v[52:53], v[62:63], v[76:77], v[52:53] op_sel_hi:[0,1,1] neg_lo:[0,0,1] neg_hi:[0,0,1]
	v_cvt_pk_bf16_f32 v16, v54, s0
	v_cvt_pk_bf16_f32 v23, v55, s0
	v_pk_mul_f32 v[54:55], v[60:61], v[76:77] op_sel:[1,0]
	v_pk_fma_f32 v[56:57], v[62:63], v[82:83], v[56:57] op_sel_hi:[0,1,1]
	v_pk_mul_f32 v[58:59], v[68:69], v[82:83] op_sel:[1,0]
	v_perm_b32 v50, v4, v0, s37
	v_cvt_pk_bf16_f32 v0, v52, s0
	v_cvt_pk_bf16_f32 v4, v53, s0
	v_perm_b32 v53, v23, v16, s37
	v_pk_fma_f32 v[54:55], v[62:63], v[78:79], v[54:55] op_sel_hi:[0,1,1]
	v_cvt_pk_bf16_f32 v16, v56, s0
	v_cvt_pk_bf16_f32 v23, v57, s0
	v_pk_mul_f32 v[56:57], v[68:69], v[78:79] op_sel:[1,0]
	v_pk_fma_f32 v[58:59], v[74:75], v[80:81], v[58:59] op_sel_hi:[0,1,1] neg_lo:[0,0,1] neg_hi:[0,0,1]
	v_pk_mul_f32 v[60:61], v[68:69], v[80:81] op_sel:[1,0]
	v_perm_b32 v52, v4, v0, s37
	v_cvt_pk_bf16_f32 v0, v54, s0
	v_cvt_pk_bf16_f32 v4, v55, s0
	v_perm_b32 v55, v23, v16, s37
	v_pk_fma_f32 v[56:57], v[74:75], v[76:77], v[56:57] op_sel_hi:[0,1,1] neg_lo:[0,0,1] neg_hi:[0,0,1]
	v_cvt_pk_bf16_f32 v16, v58, s0
	v_cvt_pk_bf16_f32 v23, v59, s0
	v_pk_mul_f32 v[58:59], v[68:69], v[76:77] op_sel:[1,0]
	v_pk_fma_f32 v[60:61], v[74:75], v[82:83], v[60:61] op_sel_hi:[0,1,1]
	v_pk_mul_f32 v[62:63], v[66:67], v[82:83] op_sel_hi:[0,1]
	v_perm_b32 v54, v4, v0, s37
	v_cvt_pk_bf16_f32 v0, v56, s0
	v_cvt_pk_bf16_f32 v4, v57, s0
	v_perm_b32 v57, v23, v16, s37
	v_pk_fma_f32 v[58:59], v[74:75], v[78:79], v[58:59] op_sel_hi:[0,1,1]
	v_cvt_pk_bf16_f32 v16, v60, s0
	v_cvt_pk_bf16_f32 v23, v61, s0
	v_pk_fma_f32 v[62:63], v[64:65], v[80:81], v[62:63] op_sel_hi:[0,1,1] neg_lo:[0,0,1] neg_hi:[0,0,1]
	v_perm_b32 v56, v4, v0, s37
	v_cvt_pk_bf16_f32 v4, v59, s0
	v_perm_b32 v59, v23, v16, s37
	v_pk_mul_f32 v[60:61], v[66:67], v[78:79] op_sel_hi:[0,1]
	v_cvt_pk_bf16_f32 v16, v62, s0
	v_cvt_pk_bf16_f32 v23, v63, s0
	v_pk_mul_f32 v[62:63], v[66:67], v[76:77] op_sel_hi:[0,1]
	v_pk_mul_f32 v[66:67], v[66:67], v[80:81] op_sel_hi:[0,1]
	v_cvt_pk_bf16_f32 v0, v58, s0
	v_pk_fma_f32 v[60:61], v[64:65], v[76:77], v[60:61] op_sel_hi:[0,1,1] neg_lo:[0,0,1] neg_hi:[0,0,1]
	v_pk_fma_f32 v[66:67], v[64:65], v[82:83], v[66:67] op_sel_hi:[0,1,1]
	v_perm_b32 v58, v4, v0, s37
	v_cvt_pk_bf16_f32 v4, v61, s0
	v_perm_b32 v61, v23, v16, s37
	v_cvt_pk_bf16_f32 v16, v66, s0
	v_cvt_pk_bf16_f32 v23, v67, s0
	s_waitcnt vmcnt(3)
; __device__ __forceinline__ unsigned pk2(float lo, float hi) { f32x2 v = {lo, hi}; nbf2 r = __builtin_convertvector(v, nbf2); return __builtin_bit_cast(unsigned, r); }
; __device__ __forceinline__ bf16x4 cscale_bf(const bf16x4 re, const bf16x4 im, float wr, float wi, bool want_im) {
;     bf16x4 o;
; #pragma unroll
;     for (int k = 0; k < 4; k += 2) {
;         const float r0 = __uint_as_float((unsigned)(unsigned short)re[k] << 16), r1 = __uint_as_float((unsigned)(unsigned short)re[k + 1] << 16);
;         const float i0 = __uint_as_float((unsigned)(unsigned short)im[k] << 16), i1 = __uint_as_float((unsigned)(unsigned short)im[k + 1] << 16);
;         const unsigned w = want_im ? pk2(wr * i0 + wi * r0, wr * i1 + wi * r1) : pk2(wr * r0 - wi * i0, wr * r1 - wi * i1);
;         o[k] = (short)(w & 0xffffu); o[k + 1] = (short)(w >> 16);
;     }
;     return o;
; }
; template <int DIR>
; __device__ __forceinline__ void s5_local_dir(const bf16_t* UZ, unsigned char* ws, int gw, int NGW, int lane) {
;     ...
;     for (int t = 0; t < 4; ++t) {
;         const int p = 16 * t + fr;
;         const bf16x4 b_re = *(const bf16x4*)(Bb + (2 * p) * 16 + 4 * fq), b_im = *(const bf16x4*)(Bb + (2 * p + 1) * 16 + 4 * fq);
;         const f32x4 ap = ((const f32x4*)(ws + WS_APOW))[pair * 64 + p];
;         const float ar = ap.x, ai = ap.y;
;         float r2 = ar, i2 = ai; cmul(r2, i2, ar, ai);
;         float r4 = r2, i4 = i2; cmul(r4, i4, r2, i2);
;         float r8 = r4, i8 = i4; cmul(r8, i8, r4, i4);
;         float r12 = r8, i12 = i8; cmul(r12, i12, r4, i4);
;         float r16 = r8, i16 = i8; cmul(r16, i16, r8, i8);
;         float r32 = r16, i32 = i16; cmul(r32, i32, r16, i16);
;         float r48 = r32, i48 = i32; cmul(r48, i48, r16, i16);
;         a1r[t] = ar; a1i[t] = ai; a64r[t] = ap.z; a64i[t] = ap.w;
;         const int e = DIR ? fq : 3 - fq;
;         wr_[t] = e == 0 ? 1.f : e == 1 ? r4 : e == 2 ? r8 : r12; wi_[t] = e == 0 ? 0.f : e == 1 ? i4 : e == 2 ? i8 : i12;
; #pragma unroll
;         for (int m = 0; m < 4; ++m) {
;             const int em = DIR ? m : 3 - m;
;             const float pr = em == 0 ? 1.f : em == 1 ? r16 : em == 2 ? r32 : r48, pi = em == 0 ? 0.f : em == 1 ? i16 : em == 2 ? i32 : i48;
;             Bre[m][t] = cscale_bf(b_re, b_im, pr, pi, false); Bim[m][t] = cscale_bf(b_re, b_im, pr, pi, true);
;         }
	v_pk_mul_f32 v[66:67], v[8:9], v[8:9] op_sel:[1,1] op_sel_hi:[1,0]
	v_pk_fma_f32 v[62:63], v[64:65], v[78:79], v[62:63] op_sel_hi:[0,1,1]
	v_pk_fma_f32 v[68:69], v[8:9], v[8:9], v[66:67] op_sel_hi:[1,0,1] neg_lo:[0,0,1] neg_hi:[0,0,1]
	v_pk_fma_f32 v[66:67], v[8:9], v[8:9], v[66:67] op_sel_hi:[1,0,1]
	v_mov_b32_e32 v74, v68
	v_pk_mov_b32 v[76:77], v[66:67], v[68:69] op_sel:[1,0]
	v_mov_b32_e32 v75, v67
	v_pk_mul_f32 v[66:67], v[66:67], v[76:77] op_sel:[1,0]
	v_cvt_pk_bf16_f32 v0, v60, s0
	v_pk_fma_f32 v[76:77], v[68:69], v[74:75], v[66:67] op_sel_hi:[0,1,1] neg_lo:[0,0,1] neg_hi:[0,0,1]
	v_pk_fma_f32 v[66:67], v[68:69], v[74:75], v[66:67] op_sel_hi:[0,1,1]
	v_pk_mov_b32 v[74:75], v[66:67], v[76:77] op_sel:[1,0]
	v_mov_b32_e32 v68, v76
	v_mov_b32_e32 v69, v67
	v_pk_mul_f32 v[74:75], v[66:67], v[74:75] op_sel:[1,0]
	v_perm_b32 v60, v4, v0, s37
	v_pk_fma_f32 v[78:79], v[76:77], v[68:69], v[74:75] op_sel_hi:[0,1,1] neg_lo:[0,0,1] neg_hi:[0,0,1]
	v_pk_fma_f32 v[74:75], v[76:77], v[68:69], v[74:75] op_sel_hi:[0,1,1]
	v_pk_mov_b32 v[82:83], v[74:75], v[78:79] op_sel:[1,0]
	v_mov_b32_e32 v80, v78
	v_mov_b32_e32 v81, v75
	v_pk_mul_f32 v[82:83], v[74:75], v[82:83] op_sel:[1,0]
	v_cvt_pk_bf16_f32 v0, v62, s0
	v_pk_fma_f32 v[84:85], v[78:79], v[80:81], v[82:83] op_sel_hi:[0,1,1] neg_lo:[0,0,1] neg_hi:[0,0,1]
	v_pk_fma_f32 v[82:83], v[78:79], v[80:81], v[82:83] op_sel_hi:[0,1,1]
	v_pk_mov_b32 v[88:89], v[82:83], v[84:85] op_sel:[1,0]
	v_mov_b32_e32 v86, v84
	v_mov_b32_e32 v87, v83
	v_pk_mul_f32 v[90:91], v[82:83], v[88:89] op_sel:[1,0]
	v_cvt_pk_bf16_f32 v4, v63, s0
	v_pk_fma_f32 v[96:97], v[84:85], v[86:87], v[90:91] op_sel_hi:[0,1,1] neg_lo:[0,0,1] neg_hi:[0,0,1]
	v_pk_fma_f32 v[90:91], v[84:85], v[86:87], v[90:91] op_sel_hi:[0,1,1]
	v_perm_b32 v62, v4, v0, s37
	v_mov_b32_e32 v98, v96
	v_mov_b32_e32 v99, v91
	v_mul_f32_e32 v0, v83, v91
	v_pk_fma_f32 v[86:87], v[86:87], v[98:99], v[0:1] op_sel_hi:[1,1,0] neg_lo:[0,0,1] neg_hi:[0,0,1]
	v_mul_f32_e32 v0, v84, v91
	v_pk_fma_f32 v[88:89], v[88:89], v[98:99], v[0:1] op_sel_hi:[1,1,0]
	v_mul_f32_e32 v0, v67, v78
	v_pk_mul_f32 v[68:69], v[68:69], v[80:81]
	v_fmac_f32_e32 v0, v76, v75
	v_sub_f32_e32 v4, v68, v69
	v_and_b32_e32 v101, 0xffff0000, v70
	v_lshlrev_b32_e32 v100, 16, v70
	v_and_b32_e32 v105, 0xffff0000, v71
	v_lshlrev_b32_e32 v104, 16, v71
	v_cndmask_b32_e32 v4, v4, v78, vcc
	v_cndmask_b32_e32 v0, v0, v75, vcc
	v_and_b32_e32 v99, 0xffff0000, v72
	v_lshlrev_b32_e32 v98, 16, v72
	v_and_b32_e32 v103, 0xffff0000, v73
	v_lshlrev_b32_e32 v102, 16, v73
	v_xor_b32_e32 v71, 0x80000000, v105
	v_xor_b32_e32 v70, 0x80000000, v104
	v_xor_b32_e32 v73, 0x80000000, v101
	v_xor_b32_e32 v72, 0x80000000, v100
	v_cndmask_b32_e64 v4, v4, v76, s[2:3]
	v_cndmask_b32_e64 v0, v0, v67, s[2:3]
	v_pk_fma_f32 v[70:71], v[70:71], 0, v[102:103] op_sel_hi:[1,0,1]
	v_pk_fma_f32 v[72:73], v[72:73], 0, v[98:99] op_sel_hi:[1,0,1]
	v_perm_b32 v63, v23, v16, s37
	v_mov_b32_e32 v64, v8
	v_mov_b32_e32 v65, v8
	v_cndmask_b32_e64 v66, v4, 1.0, s[8:9]
	v_cndmask_b32_e64 v69, v0, 0, s[8:9]
	v_cvt_pk_bf16_f32 v0, v72, s0
	v_cvt_pk_bf16_f32 v4, v73, s0
	v_cvt_pk_bf16_f32 v8, v70, s0
	v_cvt_pk_bf16_f32 v16, v71, s0
	v_pk_fma_f32 v[72:73], v[102:103], 0, v[104:105] op_sel_hi:[1,0,1]
	v_pk_fma_f32 v[74:75], v[98:99], 0, v[100:101] op_sel_hi:[1,0,1]
	v_pk_mul_f32 v[76:77], v[82:83], v[104:105] op_sel:[1,0]
	v_perm_b32 v71, v16, v8, s37
	v_perm_b32 v70, v4, v0, s37
	v_cvt_pk_bf16_f32 v0, v74, s0
	v_cvt_pk_bf16_f32 v4, v75, s0
	v_cvt_pk_bf16_f32 v8, v72, s0
	v_cvt_pk_bf16_f32 v16, v73, s0
	v_pk_mul_f32 v[74:75], v[82:83], v[100:101] op_sel:[1,0]
	v_pk_fma_f32 v[76:77], v[84:85], v[102:103], v[76:77] op_sel_hi:[0,1,1] neg_lo:[0,0,1] neg_hi:[0,0,1]
	v_pk_mul_f32 v[78:79], v[82:83], v[102:103] op_sel:[1,0]
	v_perm_b32 v73, v16, v8, s37
	v_pk_fma_f32 v[74:75], v[84:85], v[98:99], v[74:75] op_sel_hi:[0,1,1] neg_lo:[0,0,1] neg_hi:[0,0,1]
	v_cvt_pk_bf16_f32 v8, v76, s0
	v_cvt_pk_bf16_f32 v16, v77, s0
	v_pk_mul_f32 v[76:77], v[82:83], v[98:99] op_sel:[1,0]
	v_pk_fma_f32 v[78:79], v[84:85], v[104:105], v[78:79] op_sel_hi:[0,1,1]
	v_pk_mul_f32 v[80:81], v[90:91], v[104:105] op_sel:[1,0]
	v_perm_b32 v72, v4, v0, s37
	v_cvt_pk_bf16_f32 v0, v74, s0
	v_cvt_pk_bf16_f32 v4, v75, s0
	v_perm_b32 v75, v16, v8, s37
	v_pk_fma_f32 v[76:77], v[84:85], v[100:101], v[76:77] op_sel_hi:[0,1,1]
	v_cvt_pk_bf16_f32 v8, v78, s0
	v_cvt_pk_bf16_f32 v16, v79, s0
	v_pk_mul_f32 v[78:79], v[90:91], v[100:101] op_sel:[1,0]
	v_pk_fma_f32 v[80:81], v[96:97], v[102:103], v[80:81] op_sel_hi:[0,1,1] neg_lo:[0,0,1] neg_hi:[0,0,1]
	v_pk_mul_f32 v[82:83], v[90:91], v[102:103] op_sel:[1,0]
	v_perm_b32 v74, v4, v0, s37
	v_cvt_pk_bf16_f32 v0, v76, s0
	v_cvt_pk_bf16_f32 v4, v77, s0
	v_perm_b32 v77, v16, v8, s37
	v_pk_fma_f32 v[78:79], v[96:97], v[98:99], v[78:79] op_sel_hi:[0,1,1] neg_lo:[0,0,1] neg_hi:[0,0,1]
	v_cvt_pk_bf16_f32 v8, v80, s0
	v_cvt_pk_bf16_f32 v16, v81, s0
	v_pk_mul_f32 v[80:81], v[90:91], v[98:99] op_sel:[1,0]
	v_pk_fma_f32 v[82:83], v[96:97], v[104:105], v[82:83] op_sel_hi:[0,1,1]
	v_pk_mul_f32 v[84:85], v[88:89], v[104:105] op_sel_hi:[0,1]
	v_perm_b32 v76, v4, v0, s37
	v_cvt_pk_bf16_f32 v0, v78, s0
	v_cvt_pk_bf16_f32 v4, v79, s0
	v_perm_b32 v79, v16, v8, s37
	v_pk_fma_f32 v[80:81], v[96:97], v[100:101], v[80:81] op_sel_hi:[0,1,1]
	v_cvt_pk_bf16_f32 v8, v82, s0
	v_cvt_pk_bf16_f32 v16, v83, s0
	v_pk_fma_f32 v[84:85], v[86:87], v[102:103], v[84:85] op_sel_hi:[0,1,1] neg_lo:[0,0,1] neg_hi:[0,0,1]
	v_perm_b32 v78, v4, v0, s37
	v_cvt_pk_bf16_f32 v4, v81, s0
	v_perm_b32 v81, v16, v8, s37
	v_pk_mul_f32 v[82:83], v[88:89], v[100:101] op_sel_hi:[0,1]
	v_cvt_pk_bf16_f32 v8, v84, s0
	v_cvt_pk_bf16_f32 v16, v85, s0
	v_pk_mul_f32 v[84:85], v[88:89], v[98:99] op_sel_hi:[0,1]
	v_pk_mul_f32 v[88:89], v[88:89], v[102:103] op_sel_hi:[0,1]
	v_cvt_pk_bf16_f32 v0, v80, s0
	v_pk_fma_f32 v[82:83], v[86:87], v[98:99], v[82:83] op_sel_hi:[0,1,1] neg_lo:[0,0,1] neg_hi:[0,0,1]
	v_pk_fma_f32 v[88:89], v[86:87], v[104:105], v[88:89] op_sel_hi:[0,1,1]
	v_perm_b32 v80, v4, v0, s37
	v_cvt_pk_bf16_f32 v4, v83, s0
	v_perm_b32 v83, v16, v8, s37
	v_cvt_pk_bf16_f32 v8, v88, s0
	v_cvt_pk_bf16_f32 v16, v89, s0
	s_waitcnt vmcnt(0)
; __device__ __forceinline__ unsigned pk2(float lo, float hi) { f32x2 v = {lo, hi}; nbf2 r = __builtin_convertvector(v, nbf2); return __builtin_bit_cast(unsigned, r); }
; __device__ __forceinline__ bf16x4 cscale_bf(const bf16x4 re, const bf16x4 im, float wr, float wi, bool want_im) {
;     bf16x4 o;
; #pragma unroll
;     for (int k = 0; k < 4; k += 2) {
;         const float r0 = __uint_as_float((unsigned)(unsigned short)re[k] << 16), r1 = __uint_as_float((unsigned)(unsigned short)re[k + 1] << 16);
;         const float i0 = __uint_as_float((unsigned)(unsigned short)im[k] << 16), i1 = __uint_as_float((unsigned)(unsigned short)im[k + 1] << 16);
;         const unsigned w = want_im ? pk2(wr * i0 + wi * r0, wr * i1 + wi * r1) : pk2(wr * r0 - wi * i0, wr * r1 - wi * i1);
;         o[k] = (short)(w & 0xffffu); o[k + 1] = (short)(w >> 16);
;     }
;     return o;
; }
; template <int DIR>
; __device__ __forceinline__ void s5_local_dir(const bf16_t* UZ, unsigned char* ws, int gw, int NGW, int lane) {
;     ...
;     for (int t = 0; t < 4; ++t) {
;         const int p = 16 * t + fr;
;         const bf16x4 b_re = *(const bf16x4*)(Bb + (2 * p) * 16 + 4 * fq), b_im = *(const bf16x4*)(Bb + (2 * p + 1) * 16 + 4 * fq);
;         const f32x4 ap = ((const f32x4*)(ws + WS_APOW))[pair * 64 + p];
;         const float ar = ap.x, ai = ap.y;
;         float r2 = ar, i2 = ai; cmul(r2, i2, ar, ai);
;         float r4 = r2, i4 = i2; cmul(r4, i4, r2, i2);
;         float r8 = r4, i8 = i4; cmul(r8, i8, r4, i4);
;         float r12 = r8, i12 = i8; cmul(r12, i12, r4, i4);
;         float r16 = r8, i16 = i8; cmul(r16, i16, r8, i8);
;         float r32 = r16, i32 = i16; cmul(r32, i32, r16, i16);
;         float r48 = r32, i48 = i32; cmul(r48, i48, r16, i16);
;         a1r[t] = ar; a1i[t] = ai; a64r[t] = ap.z; a64i[t] = ap.w;
;         const int e = DIR ? fq : 3 - fq;
;         wr_[t] = e == 0 ? 1.f : e == 1 ? r4 : e == 2 ? r8 : r12; wi_[t] = e == 0 ? 0.f : e == 1 ? i4 : e == 2 ? i8 : i12;
; #pragma unroll
;         for (int m = 0; m < 4; ++m) {
;             const int em = DIR ? m : 3 - m;
;             const float pr = em == 0 ? 1.f : em == 1 ? r16 : em == 2 ? r32 : r48, pi = em == 0 ? 0.f : em == 1 ? i16 : em == 2 ? i32 : i48;
;             Bre[m][t] = cscale_bf(b_re, b_im, pr, pi, false); Bim[m][t] = cscale_bf(b_re, b_im, pr, pi, true);
;         }
	v_pk_mul_f32 v[88:89], v[12:13], v[12:13] op_sel:[1,1] op_sel_hi:[1,0]
	v_pk_fma_f32 v[84:85], v[86:87], v[100:101], v[84:85] op_sel_hi:[0,1,1]
	v_pk_fma_f32 v[90:91], v[12:13], v[12:13], v[88:89] op_sel_hi:[1,0,1] neg_lo:[0,0,1] neg_hi:[0,0,1]
	v_pk_fma_f32 v[88:89], v[12:13], v[12:13], v[88:89] op_sel_hi:[1,0,1]
	v_mov_b32_e32 v96, v90
	v_pk_mov_b32 v[98:99], v[88:89], v[90:91] op_sel:[1,0]
	v_mov_b32_e32 v97, v89
	v_pk_mul_f32 v[88:89], v[88:89], v[98:99] op_sel:[1,0]
	v_cvt_pk_bf16_f32 v0, v82, s0
	v_pk_fma_f32 v[98:99], v[90:91], v[96:97], v[88:89] op_sel_hi:[0,1,1] neg_lo:[0,0,1] neg_hi:[0,0,1]
	v_pk_fma_f32 v[88:89], v[90:91], v[96:97], v[88:89] op_sel_hi:[0,1,1]
	v_pk_mov_b32 v[96:97], v[88:89], v[98:99] op_sel:[1,0]
	v_mov_b32_e32 v90, v98
	v_mov_b32_e32 v91, v89
	v_pk_mul_f32 v[96:97], v[88:89], v[96:97] op_sel:[1,0]
	v_perm_b32 v82, v4, v0, s37
	v_pk_fma_f32 v[100:101], v[98:99], v[90:91], v[96:97] op_sel_hi:[0,1,1] neg_lo:[0,0,1] neg_hi:[0,0,1]
	v_pk_fma_f32 v[96:97], v[98:99], v[90:91], v[96:97] op_sel_hi:[0,1,1]
	v_pk_mov_b32 v[104:105], v[96:97], v[100:101] op_sel:[1,0]
	v_mov_b32_e32 v102, v100
	v_mov_b32_e32 v103, v97
	v_pk_mul_f32 v[104:105], v[96:97], v[104:105] op_sel:[1,0]
	v_cvt_pk_bf16_f32 v0, v84, s0
	v_pk_fma_f32 v[106:107], v[100:101], v[102:103], v[104:105] op_sel_hi:[0,1,1] neg_lo:[0,0,1] neg_hi:[0,0,1]
	v_pk_fma_f32 v[104:105], v[100:101], v[102:103], v[104:105] op_sel_hi:[0,1,1]
	v_pk_mov_b32 v[110:111], v[104:105], v[106:107] op_sel:[1,0]
	v_mov_b32_e32 v108, v106
	v_mov_b32_e32 v109, v105
	v_pk_mul_f32 v[112:113], v[104:105], v[110:111] op_sel:[1,0]
	v_cvt_pk_bf16_f32 v4, v85, s0
	v_pk_fma_f32 v[116:117], v[106:107], v[108:109], v[112:113] op_sel_hi:[0,1,1] neg_lo:[0,0,1] neg_hi:[0,0,1]
	v_pk_fma_f32 v[112:113], v[106:107], v[108:109], v[112:113] op_sel_hi:[0,1,1]
	v_perm_b32 v84, v4, v0, s37
	v_mov_b32_e32 v114, v116
	v_mov_b32_e32 v115, v113
	v_mul_f32_e32 v0, v105, v113
	v_pk_fma_f32 v[118:119], v[108:109], v[114:115], v[0:1] op_sel_hi:[1,1,0] neg_lo:[0,0,1] neg_hi:[0,0,1]
	v_mul_f32_e32 v0, v106, v113
	v_pk_fma_f32 v[120:121], v[110:111], v[114:115], v[0:1] op_sel_hi:[1,1,0]
	v_mul_f32_e32 v0, v89, v100
	v_pk_mul_f32 v[90:91], v[90:91], v[102:103]
	v_fmac_f32_e32 v0, v98, v97
	v_sub_f32_e32 v4, v90, v91
	v_and_b32_e32 v125, 0xffff0000, v92
	v_lshlrev_b32_e32 v124, 16, v92
	v_and_b32_e32 v135, 0xffff0000, v93
	v_lshlrev_b32_e32 v134, 16, v93
	v_cndmask_b32_e32 v4, v4, v100, vcc
	v_cndmask_b32_e32 v0, v0, v97, vcc
	v_and_b32_e32 v123, 0xffff0000, v94
	v_lshlrev_b32_e32 v122, 16, v94
	v_and_b32_e32 v133, 0xffff0000, v95
	v_lshlrev_b32_e32 v132, 16, v95
	v_xor_b32_e32 v93, 0x80000000, v135
	v_xor_b32_e32 v92, 0x80000000, v134
	v_xor_b32_e32 v95, 0x80000000, v125
	v_xor_b32_e32 v94, 0x80000000, v124
	v_cndmask_b32_e64 v4, v4, v98, s[2:3]
	v_cndmask_b32_e64 v0, v0, v89, s[2:3]
	v_pk_fma_f32 v[92:93], v[92:93], 0, v[132:133] op_sel_hi:[1,0,1]
	v_pk_fma_f32 v[94:95], v[94:95], 0, v[122:123] op_sel_hi:[1,0,1]
	v_perm_b32 v85, v16, v8, s37
	v_mov_b32_e32 v86, v12
	v_mov_b32_e32 v87, v12
	v_cndmask_b32_e64 v88, v4, 1.0, s[8:9]
	v_cndmask_b32_e64 v91, v0, 0, s[8:9]
	v_cvt_pk_bf16_f32 v0, v94, s0
	v_cvt_pk_bf16_f32 v4, v95, s0
	v_cvt_pk_bf16_f32 v8, v92, s0
	v_cvt_pk_bf16_f32 v12, v93, s0
	v_pk_fma_f32 v[94:95], v[132:133], 0, v[134:135] op_sel_hi:[1,0,1]
	v_pk_fma_f32 v[96:97], v[122:123], 0, v[124:125] op_sel_hi:[1,0,1]
	v_pk_mul_f32 v[98:99], v[104:105], v[134:135] op_sel:[1,0]
	v_perm_b32 v93, v12, v8, s37
	v_perm_b32 v92, v4, v0, s37
	v_cvt_pk_bf16_f32 v0, v96, s0
	v_cvt_pk_bf16_f32 v4, v97, s0
	v_cvt_pk_bf16_f32 v8, v94, s0
	v_cvt_pk_bf16_f32 v12, v95, s0
	v_pk_mul_f32 v[96:97], v[104:105], v[124:125] op_sel:[1,0]
	v_pk_fma_f32 v[98:99], v[106:107], v[132:133], v[98:99] op_sel_hi:[0,1,1] neg_lo:[0,0,1] neg_hi:[0,0,1]
	v_pk_mul_f32 v[100:101], v[104:105], v[132:133] op_sel:[1,0]
	v_perm_b32 v95, v12, v8, s37
	v_pk_fma_f32 v[96:97], v[106:107], v[122:123], v[96:97] op_sel_hi:[0,1,1] neg_lo:[0,0,1] neg_hi:[0,0,1]
	v_cvt_pk_bf16_f32 v8, v98, s0
	v_cvt_pk_bf16_f32 v12, v99, s0
	v_pk_mul_f32 v[98:99], v[104:105], v[122:123] op_sel:[1,0]
	v_pk_fma_f32 v[100:101], v[106:107], v[134:135], v[100:101] op_sel_hi:[0,1,1]
	v_perm_b32 v94, v4, v0, s37
	v_cvt_pk_bf16_f32 v0, v96, s0
	v_cvt_pk_bf16_f32 v4, v97, s0
	v_perm_b32 v97, v12, v8, s37
	v_pk_fma_f32 v[98:99], v[106:107], v[124:125], v[98:99] op_sel_hi:[0,1,1]
	v_cvt_pk_bf16_f32 v8, v100, s0
	v_cvt_pk_bf16_f32 v12, v101, s0
	v_pk_mul_f32 v[100:101], v[112:113], v[124:125] op_sel:[1,0]
	v_perm_b32 v96, v4, v0, s37
	v_cvt_pk_bf16_f32 v0, v98, s0
	v_cvt_pk_bf16_f32 v4, v99, s0
	v_pk_fma_f32 v[100:101], v[116:117], v[122:123], v[100:101] op_sel_hi:[0,1,1] neg_lo:[0,0,1] neg_hi:[0,0,1]
; template <int DIR>
; __device__ __forceinline__ void s5_local_dir(const bf16_t* UZ, unsigned char* ws, int gw, int NGW, int lane) {
;     ...
;     const int qd = gw >> 7, b = qd >> 2, q = qd & 3;
;     if (qd >= 16) return;
;     const int c0 = 17 * q, c1 = q < 3 ? c0 + 17 : 67;
;     float Rr[4] = {0.f, 0.f, 0.f, 0.f}, Ri[4] = {0.f, 0.f, 0.f, 0.f};
;     float* ebase = E + ((size_t)((b * 2 + DIR) * 64 + g) * NCHUNK) * 128;
;     bf16x4 Un[4];
;     load_uf(Un, UZ, chunk_rowbase(b, DIR, c0), g, lane);
;     for (int c = c0; c < c1; ++c) {
;         bf16x4 Uf[4];
; #pragma unroll
;         for (int m = 0; m < 4; ++m) Uf[m] = Un[m];
;         if (c + 1 < c1) load_uf(Un, UZ, chunk_rowbase(b, DIR, c + 1), g, lane);
;     ...
;             f32x2 s2 = {DIR ? cr[3] : cr[0], DIR ? ci[3] : ci[0]};
; #pragma unroll
;             for (int ii = 1; ii < 4; ++ii) { const int i = DIR ? 3 - ii : ii;
;                 s2 = cmac(s2, (f32x2){a1r[t], a1r[t]}, (f32x2){-a1i[t], a1i[t]}, (f32x2){cr[i], ci[i]}); }
;             s2 = cmac(s2, (f32x2){wr_[t], wr_[t]}, (f32x2){-wi_[t], wi_[t]}, (f32x2){0.f, 0.f});
;             float sr = s2.x, si = s2.y;
;             sr += __shfl_xor(sr, 16); si += __shfl_xor(si, 16); sr += __shfl_xor(sr, 32); si += __shfl_xor(si, 32);
;             if (fq == 0) { e[16 * t + fr] = Rr[t]; e[64 + 16 * t + fr] = Ri[t]; }
;             const float nr = fmaf(a64r[t], Rr[t], fmaf(-a64i[t], Ri[t], sr)), ni = fmaf(a64r[t], Ri[t], fmaf(a64i[t], Rr[t], si)); Rr[t] = nr; Ri[t] = ni;
	v_perm_b32 v98, v4, v0, s37
	v_cvt_pk_bf16_f32 v0, v100, s0
	v_cvt_pk_bf16_f32 v4, v101, s0
	s_mul_i32 s2, s43, 0xfffffbc0
	v_perm_b32 v100, v4, v0, s37
	v_or_b32_e32 v0, s2, v127
	s_cselect_b32 s2, s47, s48
	v_add_u32_e32 v106, s2, v0
	v_or_b32_e32 v110, 16, v106
	v_ashrrev_i32_e32 v111, 31, v110
	v_ashrrev_i32_e32 v107, 31, v106
	v_lshlrev_b64 v[110:111], 12, v[110:111]
	v_lshlrev_b64 v[108:109], 12, v[106:107]
	v_lshl_add_u64 v[136:137], v[18:19], 0, v[110:111]
	v_or_b32_e32 v110, 32, v106
	v_or_b32_e32 v106, 48, v106
	v_pk_mul_f32 v[102:103], v[112:113], v[134:135] op_sel:[1,0]
	v_ashrrev_i32_e32 v111, 31, v110
	v_ashrrev_i32_e32 v107, 31, v106
	v_pk_fma_f32 v[102:103], v[116:117], v[132:133], v[102:103] op_sel_hi:[0,1,1] neg_lo:[0,0,1] neg_hi:[0,0,1]
	v_lshl_add_u64 v[108:109], v[18:19], 0, v[108:109]
	v_lshlrev_b64 v[110:111], 12, v[110:111]
	v_lshlrev_b64 v[106:107], 12, v[106:107]
	v_perm_b32 v99, v12, v8, s37
	v_cvt_pk_bf16_f32 v8, v102, s0
	v_cvt_pk_bf16_f32 v12, v103, s0
	v_pk_mul_f32 v[102:103], v[112:113], v[122:123] op_sel:[1,0]
	v_pk_mul_f32 v[104:105], v[112:113], v[132:133] op_sel:[1,0]
	v_lshl_add_u64 v[138:139], v[18:19], 0, v[110:111]
	v_lshl_add_u64 v[106:107], v[18:19], 0, v[106:107]
	global_load_dwordx2 v[110:111], v[108:109], off
	global_load_dwordx2 v[112:113], v[136:137], off
	global_load_dwordx2 v[114:115], v[138:139], off
	s_nop 0
	global_load_dwordx2 v[108:109], v[106:107], off
	v_pk_fma_f32 v[104:105], v[116:117], v[134:135], v[104:105] op_sel_hi:[0,1,1]
	v_pk_mul_f32 v[106:107], v[120:121], v[134:135] op_sel_hi:[0,1]
	v_perm_b32 v101, v12, v8, s37
	v_pk_fma_f32 v[102:103], v[116:117], v[124:125], v[102:103] op_sel_hi:[0,1,1]
	v_cvt_pk_bf16_f32 v8, v104, s0
	v_cvt_pk_bf16_f32 v12, v105, s0
	v_pk_mul_f32 v[104:105], v[120:121], v[124:125] op_sel_hi:[0,1]
	v_pk_fma_f32 v[106:107], v[118:119], v[132:133], v[106:107] op_sel_hi:[0,1,1] neg_lo:[0,0,1] neg_hi:[0,0,1]
	v_cvt_pk_bf16_f32 v0, v102, s0
	v_cvt_pk_bf16_f32 v4, v103, s0
	v_perm_b32 v103, v12, v8, s37
	v_pk_fma_f32 v[104:105], v[118:119], v[122:123], v[104:105] op_sel_hi:[0,1,1] neg_lo:[0,0,1] neg_hi:[0,0,1]
	v_cvt_pk_bf16_f32 v8, v106, s0
	v_cvt_pk_bf16_f32 v12, v107, s0
	v_pk_mul_f32 v[106:107], v[120:121], v[122:123] op_sel_hi:[0,1]
	v_perm_b32 v102, v4, v0, s37
	v_cvt_pk_bf16_f32 v0, v104, s0
	v_cvt_pk_bf16_f32 v4, v105, s0
	v_pk_fma_f32 v[106:107], v[118:119], v[124:125], v[106:107] op_sel_hi:[0,1,1]
	v_perm_b32 v104, v4, v0, s37
	v_pk_mul_f32 v[116:117], v[120:121], v[132:133] op_sel_hi:[0,1]
	v_cvt_pk_bf16_f32 v0, v106, s0
	v_cvt_pk_bf16_f32 v4, v107, s0
	s_add_i32 s2, s45, s44
	v_pk_fma_f32 v[116:117], v[118:119], v[134:135], v[116:117] op_sel_hi:[0,1,1]
	v_perm_b32 v106, v4, v0, s37
	v_mbcnt_lo_u32_b32 v0, -1, 0
	s_add_i32 s2, s2, 64
	s_bfe_u32 s36, s40, 0x20007
	v_perm_b32 v105, v12, v8, s37
	v_cvt_pk_bf16_f32 v8, v116, s0
	v_cvt_pk_bf16_f32 v12, v117, s0
	v_mbcnt_hi_u32_b32 v0, -1, v0
	s_mul_hi_i32 s3, s2, 0x8800
	s_mul_i32 s2, s2, 0x8800
	s_mulk_i32 s36, 0x2200
	v_perm_b32 v107, v12, v8, s37
	v_and_b32_e32 v8, 64, v0
	s_add_u32 s2, s2, s36
	v_xor_b32_e32 v4, 16, v0
	v_add_u32_e32 v8, 64, v8
	s_addc_u32 s3, s3, 0
	v_cmp_lt_i32_e32 vcc, v4, v8
	s_add_u32 s2, s30, s2
	v_lshlrev_b32_e32 v16, 2, v126
	v_cndmask_b32_e32 v4, v0, v4, vcc
	s_addc_u32 s3, s31, s3
	v_lshlrev_b32_e32 v131, 2, v4
	v_xor_b32_e32 v4, 32, v0
	v_lshl_add_u64 v[116:117], s[2:3], 0, v[16:17]
	s_mov_b64 s[2:3], 0x1700100
	v_cmp_lt_i32_e32 vcc, v4, v8
	v_lshl_add_u64 v[116:117], v[116:117], 0, s[2:3]
	s_mul_i32 s2, s43, 0x440
	v_cndmask_b32_e32 v0, v0, v4, vcc
	v_subrev_u32_e32 v16, s2, v127
	v_lshlrev_b32_e32 v132, 2, v0
	v_xor_b32_e32 v0, 0x80000000, v1
	v_mov_b32_e32 v23, v22
	v_xor_b32_e32 v24, 0x80000000, v25
	v_xor_b32_e32 v4, 0x80000000, v5
	v_mov_b32_e32 v45, v44
	v_xor_b32_e32 v46, 0x80000000, v47
	v_xor_b32_e32 v8, 0x80000000, v9
	v_mov_b32_e32 v67, v66
	v_xor_b32_e32 v68, 0x80000000, v69
	v_xor_b32_e32 v12, 0x80000000, v13
	v_mov_b32_e32 v89, v88
	v_xor_b32_e32 v90, 0x80000000, v91
	v_subrev_u32_e32 v16, 32, v16
	s_mov_b64 s[2:3], 0x200
	v_mov_b32_e32 v137, v17
	v_mov_b32_e32 v135, v17
	v_mov_b32_e32 v133, v17
	v_mov_b32_e32 v139, v17
	v_mov_b32_e32 v138, v17
	v_mov_b32_e32 v136, v17
	v_mov_b32_e32 v134, v17
	v_and_b32_e32 v244, 16, v126
	v_and_b32_e32 v245, 32, v126
	v_cmp_ne_u32_e64 s[96:97], 0, v244
	v_cmp_ne_u32_e32 vcc, 0, v245
	s_nop 1
	v_cndmask_b32_e32 v244, v2, v10, vcc
	v_cndmask_b32_e32 v245, v6, v14, vcc
	v_cndmask_b32_e64 v242, v244, v245, s[96:97]
	v_cndmask_b32_e32 v244, v3, v11, vcc
	v_cndmask_b32_e32 v245, v7, v15, vcc
	v_cndmask_b32_e64 v243, v244, v245, s[96:97]

; template <int DIR>
; __device__ __forceinline__ void s5_local_dir(const bf16_t* UZ, unsigned char* ws, int gw, int NGW, int lane) {
;     ...
;     for (int c = c0; c < c1; ++c) {
;         bf16x4 Uf[4];
; #pragma unroll
;         for (int m = 0; m < 4; ++m) Uf[m] = Un[m];
;         if (c + 1 < c1) load_uf(Un, UZ, chunk_rowbase(b, DIR, c + 1), g, lane);
;         float* e = ebase + (size_t)c * 128;
; #pragma unroll
;         for (int t = 0; t < 4; ++t) {
;             f32x4 cr = {0.f, 0.f, 0.f, 0.f}, ci = {0.f, 0.f, 0.f, 0.f};
; #pragma unroll
;             for (int m = 0; m < 4; ++m) {
;                 cr = __builtin_amdgcn_mfma_f32_16x16x16bf16_1k(Uf[m], Bre[m][t], cr, 0, 0, 0);
;                 ci = __builtin_amdgcn_mfma_f32_16x16x16bf16_1k(Uf[m], Bim[m][t], ci, 0, 0, 0);
;             }
;             f32x2 s2 = {DIR ? cr[3] : cr[0], DIR ? ci[3] : ci[0]};
; #pragma unroll
;             for (int ii = 1; ii < 4; ++ii) { const int i = DIR ? 3 - ii : ii;
;                 s2 = cmac(s2, (f32x2){a1r[t], a1r[t]}, (f32x2){-a1i[t], a1i[t]}, (f32x2){cr[i], ci[i]}); }
;             s2 = cmac(s2, (f32x2){wr_[t], wr_[t]}, (f32x2){-wi_[t], wi_[t]}, (f32x2){0.f, 0.f});
;             float sr = s2.x, si = s2.y;
;             sr += __shfl_xor(sr, 16); si += __shfl_xor(si, 16); sr += __shfl_xor(sr, 32); si += __shfl_xor(si, 32);
;             if (fq == 0) { e[16 * t + fr] = Rr[t]; e[64 + 16 * t + fr] = Ri[t]; }
;             const float nr = fmaf(a64r[t], Rr[t], fmaf(-a64i[t], Ri[t], sr)), ni = fmaf(a64r[t], Ri[t], fmaf(a64i[t], Rr[t], si)); Rr[t] = nr; Ri[t] = ni;
;         }
;     }
.LBB0_652:
	global_store_dword v[116:117], v240, off offset:-256
	global_store_dword v[116:117], v241, off
	s_waitcnt vmcnt(9)
	v_mfma_f32_16x16x16_bf16 v[140:143], v[110:111], v[26:27], 0
	v_mfma_f32_16x16x16_bf16 v[144:147], v[110:111], v[28:29], 0
	s_waitcnt vmcnt(8)
	v_mfma_f32_16x16x16_bf16 v[140:143], v[112:113], v[30:31], v[140:143]
	v_mfma_f32_16x16x16_bf16 v[144:147], v[112:113], v[32:33], v[144:147]
	s_waitcnt vmcnt(7)
	v_mfma_f32_16x16x16_bf16 v[140:143], v[114:115], v[34:35], v[140:143]
	v_mfma_f32_16x16x16_bf16 v[144:147], v[114:115], v[36:37], v[144:147]
	s_waitcnt vmcnt(6)
	v_mfma_f32_16x16x16_bf16 v[140:143], v[108:109], v[38:39], v[140:143]
	v_mfma_f32_16x16x16_bf16 v[144:147], v[108:109], v[40:41], v[144:147]
	v_mfma_f32_16x16x16_bf16 v[196:199], v[110:111], v[48:49], 0
	v_mfma_f32_16x16x16_bf16 v[200:203], v[110:111], v[50:51], 0
	v_mfma_f32_16x16x16_bf16 v[196:199], v[112:113], v[52:53], v[196:199]
	v_mfma_f32_16x16x16_bf16 v[200:203], v[112:113], v[54:55], v[200:203]
	v_mfma_f32_16x16x16_bf16 v[196:199], v[114:115], v[56:57], v[196:199]
	v_mfma_f32_16x16x16_bf16 v[200:203], v[114:115], v[58:59], v[200:203]
	v_mfma_f32_16x16x16_bf16 v[196:199], v[108:109], v[60:61], v[196:199]
	v_mfma_f32_16x16x16_bf16 v[200:203], v[108:109], v[62:63], v[200:203]
	v_mfma_f32_16x16x16_bf16 v[208:211], v[110:111], v[70:71], 0
	v_mfma_f32_16x16x16_bf16 v[212:215], v[110:111], v[72:73], 0
	v_mfma_f32_16x16x16_bf16 v[208:211], v[112:113], v[74:75], v[208:211]
	v_mfma_f32_16x16x16_bf16 v[212:215], v[112:113], v[76:77], v[212:215]
	v_mfma_f32_16x16x16_bf16 v[208:211], v[114:115], v[78:79], v[208:211]
	v_mfma_f32_16x16x16_bf16 v[212:215], v[114:115], v[80:81], v[212:215]
	v_mfma_f32_16x16x16_bf16 v[208:211], v[108:109], v[82:83], v[208:211]
	v_mfma_f32_16x16x16_bf16 v[212:215], v[108:109], v[84:85], v[212:215]
	v_mfma_f32_16x16x16_bf16 v[228:231], v[110:111], v[92:93], 0
	v_mfma_f32_16x16x16_bf16 v[232:235], v[110:111], v[94:95], 0
	v_mfma_f32_16x16x16_bf16 v[228:231], v[112:113], v[96:97], v[228:231]
	v_mfma_f32_16x16x16_bf16 v[186:189], v[112:113], v[98:99], v[232:235]
	v_mfma_f32_16x16x16_bf16 v[228:231], v[114:115], v[100:101], v[228:231]
	v_mfma_f32_16x16x16_bf16 v[186:189], v[114:115], v[102:103], v[186:189]
	v_mfma_f32_16x16x16_bf16 v[228:231], v[108:109], v[104:105], v[228:231]
	v_mfma_f32_16x16x16_bf16 v[184:187], v[108:109], v[106:107], v[186:189]
	s_nop 6
	v_mov_b32_e32 v148, v143
	v_mov_b32_e32 v204, v199
	v_mov_b32_e32 v216, v211
	v_mov_b32_e32 v190, v231
	v_mov_b32_e32 v149, v147
	v_mov_b32_e32 v205, v203
	v_mov_b32_e32 v217, v215
	v_mov_b32_e32 v191, v187
	v_mov_b32_e32 v150, v142
	v_mov_b32_e32 v206, v198
	v_mov_b32_e32 v218, v210
	v_mov_b32_e32 v188, v230
	v_mov_b32_e32 v151, v146
	v_mov_b32_e32 v207, v202
	v_mov_b32_e32 v219, v214
	v_mov_b32_e32 v189, v186
	v_pk_fma_f32 v[148:149], v[20:21], v[148:149], v[150:151]
	v_pk_fma_f32 v[204:205], v[42:43], v[204:205], v[206:207]
	v_pk_fma_f32 v[216:217], v[64:65], v[216:217], v[218:219]
	v_pk_fma_f32 v[188:189], v[86:87], v[190:191], v[188:189]
	v_mov_b32_e32 v142, v147
	v_mov_b32_e32 v198, v203
	v_mov_b32_e32 v210, v215
	v_mov_b32_e32 v230, v187
	v_pk_fma_f32 v[142:143], v[0:1], v[142:143], v[148:149]
	v_pk_fma_f32 v[198:199], v[4:5], v[198:199], v[204:205]
	v_pk_fma_f32 v[210:211], v[8:9], v[210:211], v[216:217]
	v_pk_fma_f32 v[186:187], v[12:13], v[230:231], v[188:189]
	v_mov_b32_e32 v146, v141
	v_mov_b32_e32 v202, v197
	v_mov_b32_e32 v214, v209
	v_mov_b32_e32 v188, v229
	v_mov_b32_e32 v147, v145
	v_mov_b32_e32 v203, v201
	v_mov_b32_e32 v215, v213
	v_mov_b32_e32 v189, v185
	v_pk_fma_f32 v[146:147], v[20:21], v[142:143], v[146:147]
	v_pk_fma_f32 v[202:203], v[42:43], v[198:199], v[202:203]
	v_pk_fma_f32 v[214:215], v[64:65], v[210:211], v[214:215]
	v_pk_fma_f32 v[188:189], v[86:87], v[186:187], v[188:189]
	v_mov_b32_e32 v141, v144
	v_mov_b32_e32 v197, v200
	v_mov_b32_e32 v209, v212
	v_mov_b32_e32 v229, v184
	v_pk_fma_f32 v[142:143], v[0:1], v[142:143], v[146:147] op_sel:[0,1,0] op_sel_hi:[1,0,1]
	v_pk_fma_f32 v[198:199], v[4:5], v[198:199], v[202:203] op_sel:[0,1,0] op_sel_hi:[1,0,1]
	v_pk_fma_f32 v[210:211], v[8:9], v[210:211], v[214:215] op_sel:[0,1,0] op_sel_hi:[1,0,1]
	v_pk_fma_f32 v[186:187], v[12:13], v[186:187], v[188:189] op_sel:[0,1,0] op_sel_hi:[1,0,1]
	s_nop 0
	s_nop 0
	s_nop 0
	s_nop 0
	v_pk_fma_f32 v[140:141], v[20:21], v[142:143], v[140:141]
	v_pk_fma_f32 v[196:197], v[42:43], v[198:199], v[196:197]
	v_pk_fma_f32 v[208:209], v[64:65], v[210:211], v[208:209]
	v_pk_fma_f32 v[184:185], v[86:87], v[186:187], v[228:229]
	s_nop 0
	s_nop 0
	s_nop 0
	s_nop 0
	v_pk_fma_f32 v[140:141], v[0:1], v[142:143], v[140:141] op_sel:[0,1,0] op_sel_hi:[1,0,1]
	v_pk_fma_f32 v[196:197], v[4:5], v[198:199], v[196:197] op_sel:[0,1,0] op_sel_hi:[1,0,1]
	v_pk_fma_f32 v[208:209], v[8:9], v[210:211], v[208:209] op_sel:[0,1,0] op_sel_hi:[1,0,1]
	v_pk_fma_f32 v[184:185], v[12:13], v[186:187], v[184:185] op_sel:[0,1,0] op_sel_hi:[1,0,1]
	s_nop 0
	s_nop 0
	s_nop 0
	s_nop 0
	v_pk_fma_f32 v[142:143], v[22:23], v[140:141], 0 op_sel_hi:[1,1,0]
	v_pk_fma_f32 v[198:199], v[44:45], v[196:197], 0 op_sel_hi:[1,1,0]
	v_pk_fma_f32 v[210:211], v[66:67], v[208:209], 0 op_sel_hi:[1,1,0]
	v_pk_fma_f32 v[186:187], v[88:89], v[184:185], 0 op_sel_hi:[1,1,0]
	s_nop 0
	s_nop 0
	s_nop 0
	s_nop 0
	v_pk_fma_f32 v[140:141], v[24:25], v[140:141], v[142:143] op_sel:[0,1,0] op_sel_hi:[1,0,1]
	v_pk_fma_f32 v[196:197], v[46:47], v[196:197], v[198:199] op_sel:[0,1,0] op_sel_hi:[1,0,1]
	v_pk_fma_f32 v[208:209], v[68:69], v[208:209], v[210:211] op_sel:[0,1,0] op_sel_hi:[1,0,1]
	v_pk_fma_f32 v[184:185], v[90:91], v[184:185], v[186:187] op_sel:[0,1,0] op_sel_hi:[1,0,1]
	s_nop 1
	v_permlane32_swap_b32_e32 v140, v208
	v_permlane32_swap_b32_e32 v141, v209
	v_permlane32_swap_b32_e32 v196, v184
	v_permlane32_swap_b32_e32 v197, v185
	v_add_f32_e32 v140, v140, v208
	v_add_f32_e32 v196, v196, v184
	v_add_f32_e32 v141, v141, v209
	v_add_f32_e32 v197, v197, v185
	s_nop 0
	v_permlane16_swap_b32_e32 v140, v196
	v_permlane16_swap_b32_e32 v141, v197
	v_add_f32_e32 v140, v140, v196
	v_add_f32_e32 v141, v141, v197
	v_fma_f32 v244, -v243, v241, v140
	v_fma_f32 v245, v243, v240, v141
	v_fma_f32 v240, v242, v240, v244
	v_fma_f32 v241, v242, v241, v245
	v_lshl_add_u64 v[116:117], v[116:117], 0, s[2:3]
	v_subrev_u32_e32 v16, 64, v16
	s_and_b64 vcc, exec, s[36:37]
	s_cbranch_vccnz .LBB0_684
	s_mov_b32 s38, s49
	s_waitcnt vmcnt(3)
	v_mov_b32_e32 v110, v118
	v_mov_b32_e32 v111, v119
	s_waitcnt vmcnt(2)
	v_mov_b32_e32 v112, v120
	v_mov_b32_e32 v113, v121
	s_waitcnt vmcnt(1)
	v_mov_b32_e32 v114, v122
	v_mov_b32_e32 v115, v123
	s_waitcnt vmcnt(0)
	v_mov_b32_e32 v108, v124
	v_mov_b32_e32 v109, v125
	s_branch .LBB0_649

; template <int DIR>
; __device__ __forceinline__ void s5_local_dir(const bf16_t* UZ, unsigned char* ws, int gw, int NGW, int lane) {
;     ...
;     bf16x4 Bre[4][4], Bim[4][4]; float a1r[4], a1i[4], a64r[4], a64i[4], wr_[4], wi_[4];
; #pragma unroll
;     for (int t = 0; t < 4; ++t) {
;         const int p = 16 * t + fr;
;         const bf16x4 b_re = *(const bf16x4*)(Bb + (2 * p) * 16 + 4 * fq), b_im = *(const bf16x4*)(Bb + (2 * p + 1) * 16 + 4 * fq);
;         const f32x4 ap = ((const f32x4*)(ws + WS_APOW))[pair * 64 + p];
;         const float ar = ap.x, ai = ap.y;
;         float r2 = ar, i2 = ai; cmul(r2, i2, ar, ai);
;         float r4 = r2, i4 = i2; cmul(r4, i4, r2, i2);
;         float r8 = r4, i8 = i4; cmul(r8, i8, r4, i4);
;         float r12 = r8, i12 = i8; cmul(r12, i12, r4, i4);
;         float r16 = r8, i16 = i8; cmul(r16, i16, r8, i8);
;         float r32 = r16, i32 = i16; cmul(r32, i32, r16, i16);
;         float r48 = r32, i48 = i32; cmul(r48, i48, r16, i16);
;         a1r[t] = ar; a1i[t] = ai; a64r[t] = ap.z; a64i[t] = ap.w;
;         const int e = DIR ? fq : 3 - fq;
;         wr_[t] = e == 0 ? 1.f : e == 1 ? r4 : e == 2 ? r8 : r12; wi_[t] = e == 0 ? 0.f : e == 1 ? i4 : e == 2 ? i8 : i12;
; #pragma unroll
;         for (int m = 0; m < 4; ++m) {
;             const int em = DIR ? m : 3 - m;
;             const float pr = em == 0 ? 1.f : em == 1 ? r16 : em == 2 ? r32 : r48, pi = em == 0 ? 0.f : em == 1 ? i16 : em == 2 ? i32 : i48;
;             Bre[m][t] = cscale_bf(b_re, b_im, pr, pi, false); Bim[m][t] = cscale_bf(b_re, b_im, pr, pi, true);
;         }
;     }
;     const int qd = gw >> 7, b = qd >> 2, q = qd & 3;
;     if (qd >= 16) return;
;     const int c0 = 17 * q, c1 = q < 3 ? c0 + 17 : 67;
;     float Rr[4] = {0.f, 0.f, 0.f, 0.f}, Ri[4] = {0.f, 0.f, 0.f, 0.f};
.LBB0_669:
	s_mul_i32 s24, s37, 17
	s_add_i32 s4, s24, 17
	s_cmp_lg_u32 s37, 3
	s_cselect_b64 s[8:9], -1, 0
	s_and_b64 s[2:3], s[8:9], exec
	s_cselect_b32 s39, s4, 0x43
	s_lshl_b32 s38, s23, 7
	v_mov_b32_e32 v115, 0
	v_mov_b32_e32 v240, 0
	v_mov_b32_e32 v241, 0
	s_cmp_ge_u32 s24, s39
	v_mov_b32_e32 v114, 0
	v_mov_b32_e32 v112, 0
	v_mov_b32_e32 v110, 0
	v_mov_b32_e32 v113, 0
	v_mov_b32_e32 v111, 0
	v_mov_b32_e32 v109, 0
	v_mov_b32_e32 v108, 0
	s_cbranch_scc1 .LBB0_702
	s_waitcnt vmcnt(9)
	v_pk_mul_f32 v[22:23], v[0:1], v[0:1] op_sel:[1,1] op_sel_hi:[1,0]
	s_lshl_b32 s2, s36, 5
	v_pk_fma_f32 v[24:25], v[0:1], v[0:1], v[22:23] op_sel_hi:[1,0,1] neg_lo:[0,0,1] neg_hi:[0,0,1]
	v_pk_fma_f32 v[22:23], v[0:1], v[0:1], v[22:23] op_sel_hi:[1,0,1]
	v_mov_b32_e32 v30, v24
	v_pk_mov_b32 v[32:33], v[22:23], v[24:25] op_sel:[1,0]
	v_mov_b32_e32 v31, v23
	v_pk_mul_f32 v[22:23], v[22:23], v[32:33] op_sel:[1,0]
	v_mov_b32_e32 v18, v0
	v_pk_fma_f32 v[32:33], v[24:25], v[30:31], v[22:23] op_sel_hi:[0,1,1] neg_lo:[0,0,1] neg_hi:[0,0,1]
	v_pk_fma_f32 v[22:23], v[24:25], v[30:31], v[22:23] op_sel_hi:[0,1,1]
	v_pk_mov_b32 v[30:31], v[22:23], v[32:33] op_sel:[1,0]
	v_mov_b32_e32 v24, v32
	v_mov_b32_e32 v25, v23
	v_pk_mul_f32 v[30:31], v[22:23], v[30:31] op_sel:[1,0]
	v_mov_b32_e32 v19, v0
	v_pk_fma_f32 v[34:35], v[32:33], v[24:25], v[30:31] op_sel_hi:[0,1,1] neg_lo:[0,0,1] neg_hi:[0,0,1]
	v_pk_fma_f32 v[30:31], v[32:33], v[24:25], v[30:31] op_sel_hi:[0,1,1]
	v_mov_b32_e32 v35, v31
	v_pk_mul_f32 v[36:37], v[34:35], v[34:35]
	v_pk_mul_f32 v[38:39], v[30:31], v[34:35] op_sel:[1,0] op_sel_hi:[0,1]
	v_mov_b32_e32 v40, v36
	v_mov_b32_e32 v41, v38
	v_pk_mov_b32 v[36:37], v[36:37], v[38:39] op_sel:[1,0]
	s_add_u32 s2, s18, s2
	v_pk_add_f32 v[38:39], v[40:41], v[36:37] neg_lo:[0,1] neg_hi:[0,1]
	v_pk_add_f32 v[36:37], v[40:41], v[36:37]
	v_mov_b32_e32 v40, v38
	v_mov_b32_e32 v41, v37
	v_pk_mul_f32 v[44:45], v[40:41], v[40:41]
	v_pk_mul_f32 v[46:47], v[36:37], v[40:41] op_sel:[1,0] op_sel_hi:[0,1]
	v_mov_b32_e32 v52, v44
	v_mov_b32_e32 v53, v46
	v_pk_mov_b32 v[44:45], v[44:45], v[46:47] op_sel:[1,0]
	v_lshrrev_b32_e32 v16, 1, v192
	v_pk_add_f32 v[46:47], v[52:53], v[44:45] neg_lo:[0,1] neg_hi:[0,1]
	v_pk_add_f32 v[44:45], v[52:53], v[44:45]
	v_mov_b32_e32 v52, v46
	v_mov_b32_e32 v53, v45
	v_mul_f32_e32 v0, v37, v45
	v_pk_mov_b32 v[42:43], v[36:37], v[38:39] op_sel:[1,0]
	v_pk_fma_f32 v[40:41], v[40:41], v[52:53], v[0:1] op_sel_hi:[1,1,0] neg_lo:[0,0,1] neg_hi:[0,0,1]
	v_mul_f32_e32 v0, v38, v45
	s_addc_u32 s3, s19, 0
	v_and_b32_e32 v20, 24, v16
	v_mov_b32_e32 v21, 0
	v_pk_fma_f32 v[42:43], v[42:43], v[52:53], v[0:1] op_sel_hi:[1,1,0]
	v_mul_f32_e32 v0, v23, v34
	v_pk_mul_f32 v[24:25], v[24:25], v[34:35]
	v_and_b32_e32 v59, 0xffff0000, v27
	v_lshlrev_b32_e32 v58, 16, v27
	v_lshl_add_u64 v[16:17], s[2:3], 0, v[20:21]
	v_fmac_f32_e32 v0, v32, v31
	v_sub_f32_e32 v20, v24, v25
	v_cmp_eq_u32_e32 vcc, 1, v128
	v_and_b32_e32 v53, 0xffff0000, v28
	v_lshlrev_b32_e32 v52, 16, v28
	v_and_b32_e32 v55, 0xffff0000, v26
	v_lshlrev_b32_e32 v54, 16, v26
	v_and_b32_e32 v57, 0xffff0000, v29
	v_lshlrev_b32_e32 v56, 16, v29
	v_pk_mul_f32 v[28:29], v[42:43], v[58:59] op_sel_hi:[0,1]
	v_cndmask_b32_e32 v20, v20, v34, vcc
	v_cmp_eq_u32_e64 s[2:3], 2, v128
	v_cndmask_b32_e32 v0, v0, v31, vcc
	v_pk_mul_f32 v[26:27], v[42:43], v[54:55] op_sel_hi:[0,1]
	v_pk_fma_f32 v[28:29], v[40:41], v[56:57], v[28:29] op_sel_hi:[0,1,1] neg_lo:[0,0,1] neg_hi:[0,0,1]
	v_pk_mul_f32 v[30:31], v[42:43], v[56:57] op_sel_hi:[0,1]
	v_cndmask_b32_e64 v20, v20, v32, s[2:3]
	v_cndmask_b32_e64 v0, v0, v23, s[2:3]
	v_cmp_eq_u32_e64 s[4:5], 3, v128
	v_pk_fma_f32 v[26:27], v[40:41], v[52:53], v[26:27] op_sel_hi:[0,1,1] neg_lo:[0,0,1] neg_hi:[0,0,1]
	v_cvt_pk_bf16_f32 v23, v28, s0
	v_cvt_pk_bf16_f32 v24, v29, s0
	s_mov_b32 s41, 0x5040100
	v_pk_mul_f32 v[28:29], v[42:43], v[52:53] op_sel_hi:[0,1]
	v_pk_fma_f32 v[30:31], v[40:41], v[58:59], v[30:31] op_sel_hi:[0,1,1]
	v_pk_mul_f32 v[32:33], v[44:45], v[58:59] op_sel:[1,0]
	v_cndmask_b32_e64 v22, v20, 1.0, s[4:5]
	v_cndmask_b32_e64 v25, v0, 0, s[4:5]
	v_cvt_pk_bf16_f32 v0, v26, s0
	v_cvt_pk_bf16_f32 v20, v27, s0
	v_perm_b32 v27, v24, v23, s41
	v_pk_fma_f32 v[28:29], v[40:41], v[54:55], v[28:29] op_sel_hi:[0,1,1]
	v_cvt_pk_bf16_f32 v23, v30, s0
	v_cvt_pk_bf16_f32 v24, v31, s0
	v_pk_mul_f32 v[30:31], v[44:45], v[54:55] op_sel:[1,0]
	v_pk_fma_f32 v[32:33], v[46:47], v[56:57], v[32:33] op_sel_hi:[0,1,1] neg_lo:[0,0,1] neg_hi:[0,0,1]
	v_pk_mul_f32 v[34:35], v[44:45], v[56:57] op_sel:[1,0]
	v_perm_b32 v26, v20, v0, s41
	v_cvt_pk_bf16_f32 v0, v28, s0
	v_cvt_pk_bf16_f32 v20, v29, s0
	v_perm_b32 v29, v24, v23, s41
	v_pk_fma_f32 v[30:31], v[46:47], v[52:53], v[30:31] op_sel_hi:[0,1,1] neg_lo:[0,0,1] neg_hi:[0,0,1]
	v_cvt_pk_bf16_f32 v23, v32, s0
	v_cvt_pk_bf16_f32 v24, v33, s0
	v_pk_mul_f32 v[32:33], v[44:45], v[52:53] op_sel:[1,0]
	v_pk_fma_f32 v[34:35], v[46:47], v[58:59], v[34:35] op_sel_hi:[0,1,1]
	v_pk_mul_f32 v[40:41], v[36:37], v[58:59] op_sel:[1,0]
	v_perm_b32 v28, v20, v0, s41
	v_cvt_pk_bf16_f32 v0, v30, s0
	v_cvt_pk_bf16_f32 v20, v31, s0
	v_perm_b32 v31, v24, v23, s41
	v_pk_fma_f32 v[32:33], v[46:47], v[54:55], v[32:33] op_sel_hi:[0,1,1]
	v_cvt_pk_bf16_f32 v23, v34, s0
	v_cvt_pk_bf16_f32 v24, v35, s0
	v_pk_fma_f32 v[40:41], v[38:39], v[56:57], v[40:41] op_sel_hi:[0,1,1] neg_lo:[0,0,1] neg_hi:[0,0,1]
	s_waitcnt vmcnt(6)
; template <int DIR>
; __device__ __forceinline__ void s5_local_dir(const bf16_t* UZ, unsigned char* ws, int gw, int NGW, int lane) {
;     ...
;     for (int t = 0; t < 4; ++t) {
;         const int p = 16 * t + fr;
;         const bf16x4 b_re = *(const bf16x4*)(Bb + (2 * p) * 16 + 4 * fq), b_im = *(const bf16x4*)(Bb + (2 * p + 1) * 16 + 4 * fq);
;         const f32x4 ap = ((const f32x4*)(ws + WS_APOW))[pair * 64 + p];
;         const float ar = ap.x, ai = ap.y;
;         float r2 = ar, i2 = ai; cmul(r2, i2, ar, ai);
;         float r4 = r2, i4 = i2; cmul(r4, i4, r2, i2);
;         float r8 = r4, i8 = i4; cmul(r8, i8, r4, i4);
;         float r12 = r8, i12 = i8; cmul(r12, i12, r4, i4);
;         float r16 = r8, i16 = i8; cmul(r16, i16, r8, i8);
;         float r32 = r16, i32 = i16; cmul(r32, i32, r16, i16);
;         float r48 = r32, i48 = i32; cmul(r48, i48, r16, i16);
;         a1r[t] = ar; a1i[t] = ai; a64r[t] = ap.z; a64i[t] = ap.w;
;         const int e = DIR ? fq : 3 - fq;
;         wr_[t] = e == 0 ? 1.f : e == 1 ? r4 : e == 2 ? r8 : r12; wi_[t] = e == 0 ? 0.f : e == 1 ? i4 : e == 2 ? i8 : i12;
; #pragma unroll
;         for (int m = 0; m < 4; ++m) {
;             const int em = DIR ? m : 3 - m;
;             const float pr = em == 0 ? 1.f : em == 1 ? r16 : em == 2 ? r32 : r48, pi = em == 0 ? 0.f : em == 1 ? i16 : em == 2 ? i32 : i48;
;             Bre[m][t] = cscale_bf(b_re, b_im, pr, pi, false); Bim[m][t] = cscale_bf(b_re, b_im, pr, pi, true);
;         }
	v_pk_mul_f32 v[44:45], v[4:5], v[4:5] op_sel:[1,1] op_sel_hi:[1,0]
	v_perm_b32 v30, v20, v0, s41
	v_cvt_pk_bf16_f32 v20, v33, s0
	v_perm_b32 v33, v24, v23, s41
	v_pk_mul_f32 v[34:35], v[36:37], v[54:55] op_sel:[1,0]
	v_cvt_pk_bf16_f32 v23, v40, s0
	v_cvt_pk_bf16_f32 v24, v41, s0
	v_pk_mul_f32 v[40:41], v[36:37], v[52:53] op_sel:[1,0]
	v_pk_mul_f32 v[36:37], v[36:37], v[56:57] op_sel:[1,0]
	v_pk_fma_f32 v[46:47], v[4:5], v[4:5], v[44:45] op_sel_hi:[1,0,1] neg_lo:[0,0,1] neg_hi:[0,0,1]
	v_pk_fma_f32 v[44:45], v[4:5], v[4:5], v[44:45] op_sel_hi:[1,0,1]
	v_pk_fma_f32 v[34:35], v[38:39], v[52:53], v[34:35] op_sel_hi:[0,1,1] neg_lo:[0,0,1] neg_hi:[0,0,1]
	v_pk_fma_f32 v[36:37], v[38:39], v[58:59], v[36:37] op_sel_hi:[0,1,1]
	v_pk_fma_f32 v[38:39], v[38:39], v[54:55], v[40:41] op_sel_hi:[0,1,1]
	v_xor_b32_e32 v41, 0x80000000, v55
	v_xor_b32_e32 v40, 0x80000000, v54
	v_pk_fma_f32 v[42:43], v[52:53], 0, v[54:55] op_sel_hi:[1,0,1]
	v_pk_mov_b32 v[54:55], v[44:45], v[46:47] op_sel:[1,0]
	v_pk_fma_f32 v[40:41], v[40:41], 0, v[52:53] op_sel_hi:[1,0,1]
	v_mov_b32_e32 v52, v46
	v_mov_b32_e32 v53, v45
	v_pk_mul_f32 v[44:45], v[44:45], v[54:55] op_sel:[1,0]
	v_cvt_pk_bf16_f32 v0, v32, s0
	v_pk_fma_f32 v[54:55], v[46:47], v[52:53], v[44:45] op_sel_hi:[0,1,1] neg_lo:[0,0,1] neg_hi:[0,0,1]
	v_pk_fma_f32 v[44:45], v[46:47], v[52:53], v[44:45] op_sel_hi:[0,1,1]
	v_perm_b32 v32, v20, v0, s41
	v_cvt_pk_bf16_f32 v0, v34, s0
	v_cvt_pk_bf16_f32 v20, v35, s0
	v_pk_mov_b32 v[52:53], v[44:45], v[54:55] op_sel:[1,0]
	v_perm_b32 v34, v20, v0, s41
	v_cvt_pk_bf16_f32 v0, v38, s0
	v_cvt_pk_bf16_f32 v20, v39, s0
	v_xor_b32_e32 v39, 0x80000000, v59
	v_xor_b32_e32 v38, 0x80000000, v58
	v_mov_b32_e32 v46, v54
	v_mov_b32_e32 v47, v45
	v_pk_mul_f32 v[52:53], v[44:45], v[52:53] op_sel:[1,0]
	v_perm_b32 v35, v24, v23, s41
	v_cvt_pk_bf16_f32 v23, v36, s0
	v_perm_b32 v36, v20, v0, s41
	v_pk_fma_f32 v[38:39], v[38:39], 0, v[56:57] op_sel_hi:[1,0,1]
	v_cvt_pk_bf16_f32 v0, v40, s0
	v_cvt_pk_bf16_f32 v20, v41, s0
	v_pk_fma_f32 v[40:41], v[56:57], 0, v[58:59] op_sel_hi:[1,0,1]
	v_pk_fma_f32 v[56:57], v[54:55], v[46:47], v[52:53] op_sel_hi:[0,1,1] neg_lo:[0,0,1] neg_hi:[0,0,1]
	v_pk_fma_f32 v[52:53], v[54:55], v[46:47], v[52:53] op_sel_hi:[0,1,1]
	v_mov_b32_e32 v57, v53
	v_pk_mul_f32 v[58:59], v[56:57], v[56:57]
	v_pk_mul_f32 v[60:61], v[52:53], v[56:57] op_sel:[1,0] op_sel_hi:[0,1]
	v_mov_b32_e32 v62, v58
	v_mov_b32_e32 v63, v60
	v_pk_mov_b32 v[58:59], v[58:59], v[60:61] op_sel:[1,0]
	v_cvt_pk_bf16_f32 v24, v37, s0
	v_pk_add_f32 v[60:61], v[62:63], v[58:59] neg_lo:[0,1] neg_hi:[0,1]
	v_pk_add_f32 v[58:59], v[62:63], v[58:59]
	v_mov_b32_e32 v62, v60
	v_mov_b32_e32 v63, v59
	v_pk_mul_f32 v[66:67], v[62:63], v[62:63]
	v_pk_mul_f32 v[68:69], v[58:59], v[62:63] op_sel:[1,0] op_sel_hi:[0,1]
	v_mov_b32_e32 v74, v66
	v_mov_b32_e32 v75, v68
	v_pk_mov_b32 v[66:67], v[66:67], v[68:69] op_sel:[1,0]
	v_perm_b32 v37, v24, v23, s41
	v_cvt_pk_bf16_f32 v23, v38, s0
	v_cvt_pk_bf16_f32 v24, v39, s0
	v_perm_b32 v38, v20, v0, s41
	v_cvt_pk_bf16_f32 v0, v42, s0
	v_cvt_pk_bf16_f32 v20, v43, s0
	v_pk_add_f32 v[68:69], v[74:75], v[66:67] neg_lo:[0,1] neg_hi:[0,1]
	v_pk_add_f32 v[66:67], v[74:75], v[66:67]
	v_perm_b32 v39, v24, v23, s41
	v_cvt_pk_bf16_f32 v23, v40, s0
	v_perm_b32 v40, v20, v0, s41
	v_mov_b32_e32 v74, v68
	v_mov_b32_e32 v75, v67
	v_mul_f32_e32 v0, v59, v67
	v_pk_mov_b32 v[64:65], v[58:59], v[60:61] op_sel:[1,0]
	v_pk_fma_f32 v[62:63], v[62:63], v[74:75], v[0:1] op_sel_hi:[1,1,0] neg_lo:[0,0,1] neg_hi:[0,0,1]
	v_mul_f32_e32 v0, v60, v67
	v_pk_fma_f32 v[64:65], v[64:65], v[74:75], v[0:1] op_sel_hi:[1,1,0]
	v_mul_f32_e32 v0, v45, v56
	v_pk_mul_f32 v[46:47], v[46:47], v[56:57]
	v_and_b32_e32 v81, 0xffff0000, v51
	v_lshlrev_b32_e32 v80, 16, v51
	v_mov_b32_e32 v42, v4
	v_mov_b32_e32 v43, v4
	v_fmac_f32_e32 v0, v54, v53
	v_sub_f32_e32 v4, v46, v47
	v_and_b32_e32 v77, 0xffff0000, v50
	v_lshlrev_b32_e32 v76, 16, v50
	v_and_b32_e32 v79, 0xffff0000, v49
	v_lshlrev_b32_e32 v78, 16, v49
	v_pk_mul_f32 v[50:51], v[64:65], v[80:81] op_sel_hi:[0,1]
	v_cvt_pk_bf16_f32 v24, v41, s0
	v_cndmask_b32_e32 v4, v4, v56, vcc
	v_cndmask_b32_e32 v0, v0, v53, vcc
	v_and_b32_e32 v75, 0xffff0000, v48
	v_lshlrev_b32_e32 v74, 16, v48
	v_pk_mul_f32 v[48:49], v[64:65], v[76:77] op_sel_hi:[0,1]
	v_pk_fma_f32 v[50:51], v[62:63], v[78:79], v[50:51] op_sel_hi:[0,1,1] neg_lo:[0,0,1] neg_hi:[0,0,1]
	v_pk_mul_f32 v[52:53], v[64:65], v[78:79] op_sel_hi:[0,1]
	v_perm_b32 v41, v24, v23, s41
	v_cndmask_b32_e64 v4, v4, v54, s[2:3]
	v_cndmask_b32_e64 v0, v0, v45, s[2:3]
	v_pk_fma_f32 v[48:49], v[62:63], v[74:75], v[48:49] op_sel_hi:[0,1,1] neg_lo:[0,0,1] neg_hi:[0,0,1]
	v_cvt_pk_bf16_f32 v20, v50, s0
	v_cvt_pk_bf16_f32 v23, v51, s0
	v_pk_mul_f32 v[50:51], v[64:65], v[74:75] op_sel_hi:[0,1]
	v_pk_fma_f32 v[52:53], v[62:63], v[80:81], v[52:53] op_sel_hi:[0,1,1]
	v_pk_mul_f32 v[54:55], v[66:67], v[80:81] op_sel:[1,0]
	v_cndmask_b32_e64 v44, v4, 1.0, s[4:5]
	v_cndmask_b32_e64 v47, v0, 0, s[4:5]
	v_cvt_pk_bf16_f32 v0, v48, s0
	v_cvt_pk_bf16_f32 v4, v49, s0
	v_perm_b32 v49, v23, v20, s41
	v_pk_fma_f32 v[50:51], v[62:63], v[76:77], v[50:51] op_sel_hi:[0,1,1]
	v_cvt_pk_bf16_f32 v20, v52, s0
	v_cvt_pk_bf16_f32 v23, v53, s0
	v_pk_mul_f32 v[52:53], v[66:67], v[76:77] op_sel:[1,0]
	v_pk_fma_f32 v[54:55], v[68:69], v[78:79], v[54:55] op_sel_hi:[0,1,1] neg_lo:[0,0,1] neg_hi:[0,0,1]
	v_pk_mul_f32 v[56:57], v[66:67], v[78:79] op_sel:[1,0]
	v_perm_b32 v48, v4, v0, s41
	v_cvt_pk_bf16_f32 v0, v50, s0
	v_cvt_pk_bf16_f32 v4, v51, s0
	v_perm_b32 v51, v23, v20, s41
	v_pk_fma_f32 v[52:53], v[68:69], v[74:75], v[52:53] op_sel_hi:[0,1,1] neg_lo:[0,0,1] neg_hi:[0,0,1]
	v_cvt_pk_bf16_f32 v20, v54, s0
	v_cvt_pk_bf16_f32 v23, v55, s0
	v_pk_mul_f32 v[54:55], v[66:67], v[74:75] op_sel:[1,0]
	v_pk_fma_f32 v[56:57], v[68:69], v[80:81], v[56:57] op_sel_hi:[0,1,1]
	v_pk_mul_f32 v[62:63], v[58:59], v[80:81] op_sel:[1,0]
	v_perm_b32 v50, v4, v0, s41
	v_cvt_pk_bf16_f32 v0, v52, s0
	v_cvt_pk_bf16_f32 v4, v53, s0
	v_perm_b32 v53, v23, v20, s41
	v_pk_fma_f32 v[54:55], v[68:69], v[76:77], v[54:55] op_sel_hi:[0,1,1]
	v_cvt_pk_bf16_f32 v20, v56, s0
	v_cvt_pk_bf16_f32 v23, v57, s0
	v_pk_fma_f32 v[62:63], v[60:61], v[78:79], v[62:63] op_sel_hi:[0,1,1] neg_lo:[0,0,1] neg_hi:[0,0,1]
	s_waitcnt vmcnt(3)
; template <int DIR>
; __device__ __forceinline__ void s5_local_dir(const bf16_t* UZ, unsigned char* ws, int gw, int NGW, int lane) {
;     ...
;     for (int t = 0; t < 4; ++t) {
;         const int p = 16 * t + fr;
;         const bf16x4 b_re = *(const bf16x4*)(Bb + (2 * p) * 16 + 4 * fq), b_im = *(const bf16x4*)(Bb + (2 * p + 1) * 16 + 4 * fq);
;         const f32x4 ap = ((const f32x4*)(ws + WS_APOW))[pair * 64 + p];
;         const float ar = ap.x, ai = ap.y;
;         float r2 = ar, i2 = ai; cmul(r2, i2, ar, ai);
;         float r4 = r2, i4 = i2; cmul(r4, i4, r2, i2);
;         float r8 = r4, i8 = i4; cmul(r8, i8, r4, i4);
;         float r12 = r8, i12 = i8; cmul(r12, i12, r4, i4);
;         float r16 = r8, i16 = i8; cmul(r16, i16, r8, i8);
;         float r32 = r16, i32 = i16; cmul(r32, i32, r16, i16);
;         float r48 = r32, i48 = i32; cmul(r48, i48, r16, i16);
;         a1r[t] = ar; a1i[t] = ai; a64r[t] = ap.z; a64i[t] = ap.w;
;         const int e = DIR ? fq : 3 - fq;
;         wr_[t] = e == 0 ? 1.f : e == 1 ? r4 : e == 2 ? r8 : r12; wi_[t] = e == 0 ? 0.f : e == 1 ? i4 : e == 2 ? i8 : i12;
; #pragma unroll
;         for (int m = 0; m < 4; ++m) {
;             const int em = DIR ? m : 3 - m;
;             const float pr = em == 0 ? 1.f : em == 1 ? r16 : em == 2 ? r32 : r48, pi = em == 0 ? 0.f : em == 1 ? i16 : em == 2 ? i32 : i48;
;             Bre[m][t] = cscale_bf(b_re, b_im, pr, pi, false); Bim[m][t] = cscale_bf(b_re, b_im, pr, pi, true);
;         }
	v_pk_mul_f32 v[66:67], v[8:9], v[8:9] op_sel:[1,1] op_sel_hi:[1,0]
	v_perm_b32 v52, v4, v0, s41
	v_cvt_pk_bf16_f32 v4, v55, s0
	v_perm_b32 v55, v23, v20, s41
	v_pk_mul_f32 v[56:57], v[58:59], v[76:77] op_sel:[1,0]
	v_cvt_pk_bf16_f32 v20, v62, s0
	v_cvt_pk_bf16_f32 v23, v63, s0
	v_pk_mul_f32 v[62:63], v[58:59], v[74:75] op_sel:[1,0]
	v_pk_mul_f32 v[58:59], v[58:59], v[78:79] op_sel:[1,0]
	v_pk_fma_f32 v[68:69], v[8:9], v[8:9], v[66:67] op_sel_hi:[1,0,1] neg_lo:[0,0,1] neg_hi:[0,0,1]
	v_pk_fma_f32 v[66:67], v[8:9], v[8:9], v[66:67] op_sel_hi:[1,0,1]
	v_pk_fma_f32 v[56:57], v[60:61], v[74:75], v[56:57] op_sel_hi:[0,1,1] neg_lo:[0,0,1] neg_hi:[0,0,1]
	v_pk_fma_f32 v[58:59], v[60:61], v[80:81], v[58:59] op_sel_hi:[0,1,1]
	v_pk_fma_f32 v[60:61], v[60:61], v[76:77], v[62:63] op_sel_hi:[0,1,1]
	v_xor_b32_e32 v63, 0x80000000, v77
	v_xor_b32_e32 v62, 0x80000000, v76
	v_pk_fma_f32 v[64:65], v[74:75], 0, v[76:77] op_sel_hi:[1,0,1]
	v_pk_mov_b32 v[76:77], v[66:67], v[68:69] op_sel:[1,0]
	v_pk_fma_f32 v[62:63], v[62:63], 0, v[74:75] op_sel_hi:[1,0,1]
	v_mov_b32_e32 v74, v68
	v_mov_b32_e32 v75, v67
	v_pk_mul_f32 v[66:67], v[66:67], v[76:77] op_sel:[1,0]
	v_cvt_pk_bf16_f32 v0, v54, s0
	v_pk_fma_f32 v[76:77], v[68:69], v[74:75], v[66:67] op_sel_hi:[0,1,1] neg_lo:[0,0,1] neg_hi:[0,0,1]
	v_pk_fma_f32 v[66:67], v[68:69], v[74:75], v[66:67] op_sel_hi:[0,1,1]
	v_perm_b32 v54, v4, v0, s41
	v_cvt_pk_bf16_f32 v0, v56, s0
	v_cvt_pk_bf16_f32 v4, v57, s0
	v_pk_mov_b32 v[74:75], v[66:67], v[76:77] op_sel:[1,0]
	v_perm_b32 v56, v4, v0, s41
	v_cvt_pk_bf16_f32 v0, v60, s0
	v_cvt_pk_bf16_f32 v4, v61, s0
	v_xor_b32_e32 v61, 0x80000000, v81
	v_xor_b32_e32 v60, 0x80000000, v80
	v_mov_b32_e32 v68, v76
	v_mov_b32_e32 v69, v67
	v_pk_mul_f32 v[74:75], v[66:67], v[74:75] op_sel:[1,0]
	v_perm_b32 v57, v23, v20, s41
	v_cvt_pk_bf16_f32 v20, v58, s0
	v_perm_b32 v58, v4, v0, s41
	v_pk_fma_f32 v[60:61], v[60:61], 0, v[78:79] op_sel_hi:[1,0,1]
	v_cvt_pk_bf16_f32 v0, v62, s0
	v_cvt_pk_bf16_f32 v4, v63, s0
	v_pk_fma_f32 v[62:63], v[78:79], 0, v[80:81] op_sel_hi:[1,0,1]
	v_pk_fma_f32 v[78:79], v[76:77], v[68:69], v[74:75] op_sel_hi:[0,1,1] neg_lo:[0,0,1] neg_hi:[0,0,1]
	v_pk_fma_f32 v[74:75], v[76:77], v[68:69], v[74:75] op_sel_hi:[0,1,1]
	v_mov_b32_e32 v79, v75
	v_pk_mul_f32 v[80:81], v[78:79], v[78:79]
	v_pk_mul_f32 v[82:83], v[74:75], v[78:79] op_sel:[1,0] op_sel_hi:[0,1]
	v_mov_b32_e32 v84, v80
	v_mov_b32_e32 v85, v82
	v_pk_mov_b32 v[80:81], v[80:81], v[82:83] op_sel:[1,0]
	v_cvt_pk_bf16_f32 v23, v59, s0
	v_pk_add_f32 v[82:83], v[84:85], v[80:81] neg_lo:[0,1] neg_hi:[0,1]
	v_pk_add_f32 v[80:81], v[84:85], v[80:81]
	v_mov_b32_e32 v84, v82
	v_mov_b32_e32 v85, v81
	v_pk_mul_f32 v[92:93], v[84:85], v[84:85]
	v_pk_mul_f32 v[94:95], v[80:81], v[84:85] op_sel:[1,0] op_sel_hi:[0,1]
	v_mov_b32_e32 v96, v92
	v_mov_b32_e32 v97, v94
	v_pk_mov_b32 v[92:93], v[92:93], v[94:95] op_sel:[1,0]
	v_perm_b32 v59, v23, v20, s41
	v_cvt_pk_bf16_f32 v20, v60, s0
	v_cvt_pk_bf16_f32 v23, v61, s0
	v_perm_b32 v60, v4, v0, s41
	v_cvt_pk_bf16_f32 v0, v64, s0
	v_cvt_pk_bf16_f32 v4, v65, s0
	v_pk_add_f32 v[94:95], v[96:97], v[92:93] neg_lo:[0,1] neg_hi:[0,1]
	v_pk_add_f32 v[92:93], v[96:97], v[92:93]
	v_perm_b32 v61, v23, v20, s41
	v_cvt_pk_bf16_f32 v20, v62, s0
	v_perm_b32 v62, v4, v0, s41
	v_mov_b32_e32 v96, v94
	v_mov_b32_e32 v97, v93
	v_mul_f32_e32 v0, v81, v93
	v_pk_mov_b32 v[86:87], v[80:81], v[82:83] op_sel:[1,0]
	v_pk_fma_f32 v[84:85], v[84:85], v[96:97], v[0:1] op_sel_hi:[1,1,0] neg_lo:[0,0,1] neg_hi:[0,0,1]
	v_mul_f32_e32 v0, v82, v93
	v_pk_fma_f32 v[86:87], v[86:87], v[96:97], v[0:1] op_sel_hi:[1,1,0]
	v_mul_f32_e32 v0, v67, v78
	v_pk_mul_f32 v[68:69], v[68:69], v[78:79]
	v_and_b32_e32 v103, 0xffff0000, v71
	v_lshlrev_b32_e32 v102, 16, v71
	v_fmac_f32_e32 v0, v76, v75
	v_sub_f32_e32 v4, v68, v69
	v_and_b32_e32 v97, 0xffff0000, v72
	v_lshlrev_b32_e32 v96, 16, v72
	v_and_b32_e32 v99, 0xffff0000, v70
	v_lshlrev_b32_e32 v98, 16, v70
	v_and_b32_e32 v101, 0xffff0000, v73
	v_lshlrev_b32_e32 v100, 16, v73
	v_pk_mul_f32 v[72:73], v[86:87], v[102:103] op_sel_hi:[0,1]
	v_cvt_pk_bf16_f32 v23, v63, s0
	v_cndmask_b32_e32 v4, v4, v78, vcc
	v_cndmask_b32_e32 v0, v0, v75, vcc
	v_pk_mul_f32 v[70:71], v[86:87], v[98:99] op_sel_hi:[0,1]
	v_pk_fma_f32 v[72:73], v[84:85], v[100:101], v[72:73] op_sel_hi:[0,1,1] neg_lo:[0,0,1] neg_hi:[0,0,1]
	v_pk_mul_f32 v[74:75], v[86:87], v[100:101] op_sel_hi:[0,1]
	v_perm_b32 v63, v23, v20, s41
	v_mov_b32_e32 v64, v8
	v_mov_b32_e32 v65, v8
	v_cndmask_b32_e64 v4, v4, v76, s[2:3]
	v_cndmask_b32_e64 v0, v0, v67, s[2:3]
	v_pk_fma_f32 v[70:71], v[84:85], v[96:97], v[70:71] op_sel_hi:[0,1,1] neg_lo:[0,0,1] neg_hi:[0,0,1]
	v_cvt_pk_bf16_f32 v8, v72, s0
	v_cvt_pk_bf16_f32 v20, v73, s0
	v_pk_mul_f32 v[72:73], v[86:87], v[96:97] op_sel_hi:[0,1]
	v_pk_fma_f32 v[74:75], v[84:85], v[102:103], v[74:75] op_sel_hi:[0,1,1]
	v_pk_mul_f32 v[76:77], v[92:93], v[102:103] op_sel:[1,0]
	v_cndmask_b32_e64 v66, v4, 1.0, s[4:5]
	v_cndmask_b32_e64 v69, v0, 0, s[4:5]
	v_cvt_pk_bf16_f32 v0, v70, s0
	v_cvt_pk_bf16_f32 v4, v71, s0
	v_perm_b32 v71, v20, v8, s41
	v_pk_fma_f32 v[72:73], v[84:85], v[98:99], v[72:73] op_sel_hi:[0,1,1]
	v_cvt_pk_bf16_f32 v8, v74, s0
	v_cvt_pk_bf16_f32 v20, v75, s0
	v_pk_mul_f32 v[74:75], v[92:93], v[98:99] op_sel:[1,0]
	v_pk_fma_f32 v[76:77], v[94:95], v[100:101], v[76:77] op_sel_hi:[0,1,1] neg_lo:[0,0,1] neg_hi:[0,0,1]
	v_pk_mul_f32 v[78:79], v[92:93], v[100:101] op_sel:[1,0]
	v_perm_b32 v70, v4, v0, s41
	v_cvt_pk_bf16_f32 v0, v72, s0
	v_cvt_pk_bf16_f32 v4, v73, s0
	v_perm_b32 v73, v20, v8, s41
	v_pk_fma_f32 v[74:75], v[94:95], v[96:97], v[74:75] op_sel_hi:[0,1,1] neg_lo:[0,0,1] neg_hi:[0,0,1]
	v_cvt_pk_bf16_f32 v8, v76, s0
	v_cvt_pk_bf16_f32 v20, v77, s0
	v_pk_mul_f32 v[76:77], v[92:93], v[96:97] op_sel:[1,0]
	v_pk_fma_f32 v[78:79], v[94:95], v[102:103], v[78:79] op_sel_hi:[0,1,1]
	v_pk_mul_f32 v[84:85], v[80:81], v[102:103] op_sel:[1,0]
	v_perm_b32 v72, v4, v0, s41
	v_cvt_pk_bf16_f32 v0, v74, s0
	v_cvt_pk_bf16_f32 v4, v75, s0
	v_perm_b32 v75, v20, v8, s41
	v_pk_fma_f32 v[76:77], v[94:95], v[98:99], v[76:77] op_sel_hi:[0,1,1]
	v_cvt_pk_bf16_f32 v8, v78, s0
	v_cvt_pk_bf16_f32 v20, v79, s0
	v_pk_fma_f32 v[84:85], v[82:83], v[100:101], v[84:85] op_sel_hi:[0,1,1] neg_lo:[0,0,1] neg_hi:[0,0,1]
	s_waitcnt vmcnt(0)
; template <int DIR>
; __device__ __forceinline__ void s5_local_dir(const bf16_t* UZ, unsigned char* ws, int gw, int NGW, int lane) {
;     ...
;     for (int t = 0; t < 4; ++t) {
;         const int p = 16 * t + fr;
;         const bf16x4 b_re = *(const bf16x4*)(Bb + (2 * p) * 16 + 4 * fq), b_im = *(const bf16x4*)(Bb + (2 * p + 1) * 16 + 4 * fq);
;         const f32x4 ap = ((const f32x4*)(ws + WS_APOW))[pair * 64 + p];
;         const float ar = ap.x, ai = ap.y;
;         float r2 = ar, i2 = ai; cmul(r2, i2, ar, ai);
;         float r4 = r2, i4 = i2; cmul(r4, i4, r2, i2);
;         float r8 = r4, i8 = i4; cmul(r8, i8, r4, i4);
;         float r12 = r8, i12 = i8; cmul(r12, i12, r4, i4);
;         float r16 = r8, i16 = i8; cmul(r16, i16, r8, i8);
;         float r32 = r16, i32 = i16; cmul(r32, i32, r16, i16);
;         float r48 = r32, i48 = i32; cmul(r48, i48, r16, i16);
;         a1r[t] = ar; a1i[t] = ai; a64r[t] = ap.z; a64i[t] = ap.w;
;         const int e = DIR ? fq : 3 - fq;
;         wr_[t] = e == 0 ? 1.f : e == 1 ? r4 : e == 2 ? r8 : r12; wi_[t] = e == 0 ? 0.f : e == 1 ? i4 : e == 2 ? i8 : i12;
; #pragma unroll
;         for (int m = 0; m < 4; ++m) {
;             const int em = DIR ? m : 3 - m;
;             const float pr = em == 0 ? 1.f : em == 1 ? r16 : em == 2 ? r32 : r48, pi = em == 0 ? 0.f : em == 1 ? i16 : em == 2 ? i32 : i48;
;             Bre[m][t] = cscale_bf(b_re, b_im, pr, pi, false); Bim[m][t] = cscale_bf(b_re, b_im, pr, pi, true);
;         }
	v_pk_mul_f32 v[92:93], v[12:13], v[12:13] op_sel:[1,1] op_sel_hi:[1,0]
	v_perm_b32 v74, v4, v0, s41
	v_cvt_pk_bf16_f32 v4, v77, s0
	v_perm_b32 v77, v20, v8, s41
	v_pk_mul_f32 v[78:79], v[80:81], v[98:99] op_sel:[1,0]
	v_cvt_pk_bf16_f32 v8, v84, s0
	v_cvt_pk_bf16_f32 v20, v85, s0
	v_pk_mul_f32 v[84:85], v[80:81], v[96:97] op_sel:[1,0]
	v_pk_mul_f32 v[80:81], v[80:81], v[100:101] op_sel:[1,0]
	v_pk_fma_f32 v[94:95], v[12:13], v[12:13], v[92:93] op_sel_hi:[1,0,1] neg_lo:[0,0,1] neg_hi:[0,0,1]
	v_pk_fma_f32 v[92:93], v[12:13], v[12:13], v[92:93] op_sel_hi:[1,0,1]
	v_pk_fma_f32 v[78:79], v[82:83], v[96:97], v[78:79] op_sel_hi:[0,1,1] neg_lo:[0,0,1] neg_hi:[0,0,1]
	v_pk_fma_f32 v[80:81], v[82:83], v[102:103], v[80:81] op_sel_hi:[0,1,1]
	v_pk_fma_f32 v[82:83], v[82:83], v[98:99], v[84:85] op_sel_hi:[0,1,1]
	v_xor_b32_e32 v85, 0x80000000, v99
	v_xor_b32_e32 v84, 0x80000000, v98
	v_pk_fma_f32 v[86:87], v[96:97], 0, v[98:99] op_sel_hi:[1,0,1]
	v_pk_mov_b32 v[98:99], v[92:93], v[94:95] op_sel:[1,0]
	v_pk_fma_f32 v[84:85], v[84:85], 0, v[96:97] op_sel_hi:[1,0,1]
	v_mov_b32_e32 v96, v94
	v_mov_b32_e32 v97, v93
	v_pk_mul_f32 v[92:93], v[92:93], v[98:99] op_sel:[1,0]
	v_cvt_pk_bf16_f32 v0, v76, s0
	v_pk_fma_f32 v[98:99], v[94:95], v[96:97], v[92:93] op_sel_hi:[0,1,1] neg_lo:[0,0,1] neg_hi:[0,0,1]
	v_pk_fma_f32 v[92:93], v[94:95], v[96:97], v[92:93] op_sel_hi:[0,1,1]
	v_perm_b32 v76, v4, v0, s41
	v_cvt_pk_bf16_f32 v0, v78, s0
	v_cvt_pk_bf16_f32 v4, v79, s0
	v_pk_mov_b32 v[96:97], v[92:93], v[98:99] op_sel:[1,0]
	v_perm_b32 v78, v4, v0, s41
	v_cvt_pk_bf16_f32 v0, v82, s0
	v_cvt_pk_bf16_f32 v4, v83, s0
	v_xor_b32_e32 v83, 0x80000000, v103
	v_xor_b32_e32 v82, 0x80000000, v102
	v_mov_b32_e32 v94, v98
	v_mov_b32_e32 v95, v93
	v_pk_mul_f32 v[96:97], v[92:93], v[96:97] op_sel:[1,0]
	v_perm_b32 v79, v20, v8, s41
	v_cvt_pk_bf16_f32 v8, v80, s0
	v_perm_b32 v80, v4, v0, s41
	v_pk_fma_f32 v[82:83], v[82:83], 0, v[100:101] op_sel_hi:[1,0,1]
	v_cvt_pk_bf16_f32 v0, v84, s0
	v_cvt_pk_bf16_f32 v4, v85, s0
	v_pk_fma_f32 v[84:85], v[100:101], 0, v[102:103] op_sel_hi:[1,0,1]
	v_pk_fma_f32 v[100:101], v[98:99], v[94:95], v[96:97] op_sel_hi:[0,1,1] neg_lo:[0,0,1] neg_hi:[0,0,1]
	v_pk_fma_f32 v[96:97], v[98:99], v[94:95], v[96:97] op_sel_hi:[0,1,1]
	v_mov_b32_e32 v101, v97
	v_pk_mul_f32 v[102:103], v[100:101], v[100:101]
	v_pk_mul_f32 v[104:105], v[96:97], v[100:101] op_sel:[1,0] op_sel_hi:[0,1]
	v_mov_b32_e32 v106, v102
	v_mov_b32_e32 v107, v104
	v_pk_mov_b32 v[102:103], v[102:103], v[104:105] op_sel:[1,0]
	v_cvt_pk_bf16_f32 v20, v81, s0
	v_pk_add_f32 v[104:105], v[106:107], v[102:103] neg_lo:[0,1] neg_hi:[0,1]
	v_pk_add_f32 v[102:103], v[106:107], v[102:103]
	v_mov_b32_e32 v106, v104
	v_mov_b32_e32 v107, v103
	v_pk_mul_f32 v[110:111], v[106:107], v[106:107]
	v_pk_mul_f32 v[112:113], v[102:103], v[106:107] op_sel:[1,0] op_sel_hi:[0,1]
	v_mov_b32_e32 v114, v110
	v_mov_b32_e32 v115, v112
	v_pk_mov_b32 v[110:111], v[110:111], v[112:113] op_sel:[1,0]
	v_perm_b32 v81, v20, v8, s41
	v_cvt_pk_bf16_f32 v8, v82, s0
	v_cvt_pk_bf16_f32 v20, v83, s0
	v_perm_b32 v82, v4, v0, s41
	v_cvt_pk_bf16_f32 v0, v86, s0
	v_cvt_pk_bf16_f32 v4, v87, s0
	v_pk_add_f32 v[112:113], v[114:115], v[110:111] neg_lo:[0,1] neg_hi:[0,1]
	v_pk_add_f32 v[110:111], v[114:115], v[110:111]
	v_perm_b32 v83, v20, v8, s41
	v_cvt_pk_bf16_f32 v8, v84, s0
	v_perm_b32 v84, v4, v0, s41
	v_mov_b32_e32 v114, v112
	v_mov_b32_e32 v115, v111
	v_mul_f32_e32 v0, v103, v111
	v_pk_mov_b32 v[108:109], v[102:103], v[104:105] op_sel:[1,0]
	v_pk_fma_f32 v[106:107], v[106:107], v[114:115], v[0:1] op_sel_hi:[1,1,0] neg_lo:[0,0,1] neg_hi:[0,0,1]
	v_mul_f32_e32 v0, v104, v111
	v_pk_fma_f32 v[108:109], v[108:109], v[114:115], v[0:1] op_sel_hi:[1,1,0]
	v_mul_f32_e32 v0, v93, v100
	v_pk_mul_f32 v[94:95], v[94:95], v[100:101]
	v_and_b32_e32 v123, 0xffff0000, v91
	v_lshlrev_b32_e32 v122, 16, v91
	v_fmac_f32_e32 v0, v98, v97
	v_sub_f32_e32 v4, v94, v95
	v_and_b32_e32 v119, 0xffff0000, v90
	v_lshlrev_b32_e32 v118, 16, v90
	v_and_b32_e32 v121, 0xffff0000, v89
	v_lshlrev_b32_e32 v120, 16, v89
	v_pk_mul_f32 v[90:91], v[108:109], v[122:123] op_sel_hi:[0,1]
	v_cvt_pk_bf16_f32 v20, v85, s0
	v_cndmask_b32_e32 v4, v4, v100, vcc
	v_cndmask_b32_e32 v0, v0, v97, vcc
	v_and_b32_e32 v117, 0xffff0000, v88
	v_lshlrev_b32_e32 v116, 16, v88
	v_pk_mul_f32 v[88:89], v[108:109], v[118:119] op_sel_hi:[0,1]
	v_pk_fma_f32 v[90:91], v[106:107], v[120:121], v[90:91] op_sel_hi:[0,1,1] neg_lo:[0,0,1] neg_hi:[0,0,1]
	v_pk_mul_f32 v[96:97], v[108:109], v[120:121] op_sel_hi:[0,1]
	v_perm_b32 v85, v20, v8, s41
	v_mov_b32_e32 v86, v12
	v_mov_b32_e32 v87, v12
	v_cndmask_b32_e64 v4, v4, v98, s[2:3]
	v_cndmask_b32_e64 v0, v0, v93, s[2:3]
	v_pk_fma_f32 v[88:89], v[106:107], v[116:117], v[88:89] op_sel_hi:[0,1,1] neg_lo:[0,0,1] neg_hi:[0,0,1]
	v_cvt_pk_bf16_f32 v8, v90, s0
	v_cvt_pk_bf16_f32 v12, v91, s0
	v_pk_mul_f32 v[90:91], v[108:109], v[116:117] op_sel_hi:[0,1]
	v_pk_fma_f32 v[96:97], v[106:107], v[122:123], v[96:97] op_sel_hi:[0,1,1]
	v_pk_mul_f32 v[98:99], v[110:111], v[122:123] op_sel:[1,0]
	v_cndmask_b32_e64 v92, v4, 1.0, s[4:5]
	v_cndmask_b32_e64 v95, v0, 0, s[4:5]
	v_cvt_pk_bf16_f32 v0, v88, s0
	v_cvt_pk_bf16_f32 v4, v89, s0
	v_perm_b32 v89, v12, v8, s41
	v_pk_fma_f32 v[90:91], v[106:107], v[118:119], v[90:91] op_sel_hi:[0,1,1]
	v_cvt_pk_bf16_f32 v8, v96, s0
	v_cvt_pk_bf16_f32 v12, v97, s0
	v_pk_mul_f32 v[96:97], v[110:111], v[118:119] op_sel:[1,0]
; __device__ __forceinline__ void load_uf(bf16x4 (&Uf)[4], const bf16_t* UZ, int rowbase, int g, int lane) {
; #pragma unroll
;     for (int m = 0; m < 4; ++m) Uf[m] = *(const bf16x4*)(UZ + (size_t)(rowbase + 16 * m + (lane & 15)) * NUZ + 16 * g + 4 * (lane >> 4));
; }
; template <int DIR>
; __device__ __forceinline__ void s5_local_dir(const bf16_t* UZ, unsigned char* ws, int gw, int NGW, int lane) {
;     ...
;             Bre[m][t] = cscale_bf(b_re, b_im, pr, pi, false); Bim[m][t] = cscale_bf(b_re, b_im, pr, pi, true);
;         }
;     }
;     const int qd = gw >> 7, b = qd >> 2, q = qd & 3;
;     if (qd >= 16) return;
;     const int c0 = 17 * q, c1 = q < 3 ? c0 + 17 : 67;
;     float Rr[4] = {0.f, 0.f, 0.f, 0.f}, Ri[4] = {0.f, 0.f, 0.f, 0.f};
;     float* ebase = E + ((size_t)((b * 2 + DIR) * 64 + g) * NCHUNK) * 128;
;     bf16x4 Un[4];
;     load_uf(Un, UZ, chunk_rowbase(b, DIR, c0), g, lane);
	v_pk_fma_f32 v[98:99], v[112:113], v[120:121], v[98:99] op_sel_hi:[0,1,1] neg_lo:[0,0,1] neg_hi:[0,0,1]
	v_pk_mul_f32 v[100:101], v[110:111], v[120:121] op_sel:[1,0]
	v_perm_b32 v88, v4, v0, s41
	v_cvt_pk_bf16_f32 v0, v90, s0
	v_cvt_pk_bf16_f32 v4, v91, s0
	v_perm_b32 v91, v12, v8, s41
	v_pk_fma_f32 v[96:97], v[112:113], v[116:117], v[96:97] op_sel_hi:[0,1,1] neg_lo:[0,0,1] neg_hi:[0,0,1]
	v_cvt_pk_bf16_f32 v8, v98, s0
	v_cvt_pk_bf16_f32 v12, v99, s0
	v_pk_mul_f32 v[98:99], v[110:111], v[116:117] op_sel:[1,0]
	v_pk_fma_f32 v[100:101], v[112:113], v[122:123], v[100:101] op_sel_hi:[0,1,1]
	v_pk_mul_f32 v[106:107], v[102:103], v[122:123] op_sel:[1,0]
	v_perm_b32 v90, v4, v0, s41
	v_cvt_pk_bf16_f32 v0, v96, s0
	v_cvt_pk_bf16_f32 v4, v97, s0
	v_perm_b32 v97, v12, v8, s41
	v_pk_fma_f32 v[98:99], v[112:113], v[118:119], v[98:99] op_sel_hi:[0,1,1]
	v_cvt_pk_bf16_f32 v8, v100, s0
	v_cvt_pk_bf16_f32 v12, v101, s0
	v_pk_fma_f32 v[106:107], v[104:105], v[120:121], v[106:107] op_sel_hi:[0,1,1] neg_lo:[0,0,1] neg_hi:[0,0,1]
	v_perm_b32 v96, v4, v0, s41
	v_cvt_pk_bf16_f32 v4, v99, s0
	v_perm_b32 v99, v12, v8, s41
	v_pk_mul_f32 v[100:101], v[102:103], v[118:119] op_sel:[1,0]
	v_cvt_pk_bf16_f32 v8, v106, s0
	v_cvt_pk_bf16_f32 v12, v107, s0
	v_pk_mul_f32 v[106:107], v[102:103], v[116:117] op_sel:[1,0]
	v_pk_mul_f32 v[102:103], v[102:103], v[120:121] op_sel:[1,0]
	v_pk_fma_f32 v[100:101], v[104:105], v[116:117], v[100:101] op_sel_hi:[0,1,1] neg_lo:[0,0,1] neg_hi:[0,0,1]
	v_pk_fma_f32 v[102:103], v[104:105], v[122:123], v[102:103] op_sel_hi:[0,1,1]
	v_pk_fma_f32 v[104:105], v[104:105], v[118:119], v[106:107] op_sel_hi:[0,1,1]
	v_add_u32_e32 v106, s25, v127
	v_ashrrev_i32_e32 v107, 31, v106
	v_lshlrev_b64 v[106:107], 12, v[106:107]
	v_lshl_add_u64 v[106:107], v[16:17], 0, v[106:107]
	s_mov_b32 s2, 0x10000
	v_add_co_u32_e32 v124, vcc, s2, v106
	s_mov_b32 s2, 0x20000
	s_nop 0
	v_addc_co_u32_e32 v125, vcc, 0, v107, vcc
	v_add_co_u32_e32 v128, vcc, s2, v106
	s_mov_b32 s2, 0x30000
	s_nop 0
	v_addc_co_u32_e32 v129, vcc, 0, v107, vcc
	v_add_co_u32_e32 v130, vcc, s2, v106
	v_cvt_pk_bf16_f32 v0, v98, s0
	s_nop 0
	v_addc_co_u32_e32 v131, vcc, 0, v107, vcc
	global_load_dwordx2 v[108:109], v[106:107], off
	global_load_dwordx2 v[112:113], v[124:125], off
	global_load_dwordx2 v[114:115], v[128:129], off
	global_load_dwordx2 v[110:111], v[130:131], off
	v_perm_b32 v98, v4, v0, s41
	v_cvt_pk_bf16_f32 v0, v100, s0
	v_cvt_pk_bf16_f32 v4, v101, s0
	v_xor_b32_e32 v107, 0x80000000, v119
	v_xor_b32_e32 v106, 0x80000000, v118
	v_perm_b32 v100, v4, v0, s41
	v_cvt_pk_bf16_f32 v0, v104, s0
	v_cvt_pk_bf16_f32 v4, v105, s0
	v_xor_b32_e32 v105, 0x80000000, v123
	v_xor_b32_e32 v104, 0x80000000, v122
	v_pk_fma_f32 v[106:107], v[106:107], 0, v[116:117] op_sel_hi:[1,0,1]
	v_perm_b32 v101, v12, v8, s41
	v_cvt_pk_bf16_f32 v8, v102, s0
	v_cvt_pk_bf16_f32 v12, v103, s0
	v_perm_b32 v102, v4, v0, s41
	v_pk_fma_f32 v[104:105], v[104:105], 0, v[120:121] op_sel_hi:[1,0,1]
	v_cvt_pk_bf16_f32 v0, v106, s0
	v_cvt_pk_bf16_f32 v4, v107, s0
	v_pk_fma_f32 v[116:117], v[116:117], 0, v[118:119] op_sel_hi:[1,0,1]
	v_perm_b32 v103, v12, v8, s41
	v_cvt_pk_bf16_f32 v8, v104, s0
	v_cvt_pk_bf16_f32 v12, v105, s0
	v_perm_b32 v104, v4, v0, s41
	v_pk_fma_f32 v[106:107], v[120:121], 0, v[122:123] op_sel_hi:[1,0,1]
	v_cvt_pk_bf16_f32 v0, v116, s0
	v_cvt_pk_bf16_f32 v4, v117, s0
	v_perm_b32 v105, v12, v8, s41
	v_cvt_pk_bf16_f32 v8, v106, s0
	v_perm_b32 v106, v4, v0, s41
	v_mbcnt_lo_u32_b32 v0, -1, 0
	v_cvt_pk_bf16_f32 v12, v107, s0
	v_mbcnt_hi_u32_b32 v0, -1, v0
	v_perm_b32 v107, v12, v8, s41
	s_lshl_b32 s41, s23, 12
	s_lshl_b32 s42, s23, 8
	v_and_b32_e32 v8, 64, v0
	s_add_i32 s4, s38, s36
	s_bfe_u32 s23, s40, 0x20007
	s_addk_i32 s41, 0xff00
	s_addk_i32 s42, 0x4000
	v_xor_b32_e32 v4, 16, v0
	v_add_u32_e32 v8, 64, v8
	s_mul_hi_i32 s5, s4, 0x8800
	s_mul_i32 s4, s4, 0x8800
	s_mulk_i32 s23, 0x2200
	v_cmp_lt_i32_e32 vcc, v4, v8
	s_add_u32 s4, s4, s23
	s_addc_u32 s5, s5, 0
	v_cndmask_b32_e32 v4, v0, v4, vcc
	v_lshlrev_b32_e32 v128, 2, v4
	v_xor_b32_e32 v4, 32, v0
	s_add_u32 s4, s30, s4
	v_cmp_lt_i32_e32 vcc, v4, v8
	v_lshlrev_b32_e32 v20, 2, v126
	s_addc_u32 s5, s31, s5
	v_cndmask_b32_e32 v0, v0, v4, vcc
	v_lshl_add_u64 v[116:117], s[4:5], 0, v[20:21]
	s_mov_b64 s[4:5], 0x1700100
	v_or_b32_e32 v20, s22, v127
	v_lshlrev_b32_e32 v129, 2, v0
	v_cmp_gt_u32_e64 s[2:3], 16, v126
	v_xor_b32_e32 v0, 0x80000000, v1
	v_mov_b32_e32 v23, v22
	v_xor_b32_e32 v24, 0x80000000, v25
	v_xor_b32_e32 v4, 0x80000000, v5
	v_mov_b32_e32 v45, v44
	v_xor_b32_e32 v46, 0x80000000, v47
	v_xor_b32_e32 v8, 0x80000000, v9
	v_mov_b32_e32 v67, v66
	v_xor_b32_e32 v68, 0x80000000, v69
	v_xor_b32_e32 v12, 0x80000000, v13
	v_mov_b32_e32 v93, v92
	v_xor_b32_e32 v94, 0x80000000, v95
	v_lshl_add_u64 v[116:117], v[116:117], 0, s[4:5]
	v_add_u32_e32 v20, 0x70, v20
	s_mov_b64 s[4:5], 0x200
	v_mov_b32_e32 v133, v21
	v_mov_b32_e32 v131, v21
	v_mov_b32_e32 v127, v21
	v_mov_b32_e32 v135, v21
	v_mov_b32_e32 v134, v21
	v_mov_b32_e32 v132, v21
	v_mov_b32_e32 v130, v21
	v_and_b32_e32 v244, 16, v126
	v_and_b32_e32 v245, 32, v126
	v_cmp_ne_u32_e64 s[96:97], 0, v244
	v_cmp_ne_u32_e32 vcc, 0, v245
	s_nop 1
	v_cndmask_b32_e32 v244, v2, v10, vcc
	v_cndmask_b32_e32 v245, v6, v14, vcc
	v_cndmask_b32_e64 v242, v244, v245, s[96:97]
	v_cndmask_b32_e32 v244, v3, v11, vcc
	v_cndmask_b32_e32 v245, v7, v15, vcc
	v_cndmask_b32_e64 v243, v244, v245, s[96:97]

; template <int DIR>
; __device__ __forceinline__ void s5_local_dir(const bf16_t* UZ, unsigned char* ws, int gw, int NGW, int lane) {
;     ...
;     for (int c = c0; c < c1; ++c) {
;         bf16x4 Uf[4];
; #pragma unroll
;         for (int m = 0; m < 4; ++m) Uf[m] = Un[m];
;         if (c + 1 < c1) load_uf(Un, UZ, chunk_rowbase(b, DIR, c + 1), g, lane);
;         float* e = ebase + (size_t)c * 128;
; #pragma unroll
;         for (int t = 0; t < 4; ++t) {
;             f32x4 cr = {0.f, 0.f, 0.f, 0.f}, ci = {0.f, 0.f, 0.f, 0.f};
; #pragma unroll
;             for (int m = 0; m < 4; ++m) {
;                 cr = __builtin_amdgcn_mfma_f32_16x16x16bf16_1k(Uf[m], Bre[m][t], cr, 0, 0, 0);
;                 ci = __builtin_amdgcn_mfma_f32_16x16x16bf16_1k(Uf[m], Bim[m][t], ci, 0, 0, 0);
;             }
;             f32x2 s2 = {DIR ? cr[3] : cr[0], DIR ? ci[3] : ci[0]};
; #pragma unroll
;             for (int ii = 1; ii < 4; ++ii) { const int i = DIR ? 3 - ii : ii;
;                 s2 = cmac(s2, (f32x2){a1r[t], a1r[t]}, (f32x2){-a1i[t], a1i[t]}, (f32x2){cr[i], ci[i]}); }
;             s2 = cmac(s2, (f32x2){wr_[t], wr_[t]}, (f32x2){-wi_[t], wi_[t]}, (f32x2){0.f, 0.f});
;             float sr = s2.x, si = s2.y;
;             sr += __shfl_xor(sr, 16); si += __shfl_xor(si, 16); sr += __shfl_xor(sr, 32); si += __shfl_xor(si, 32);
;             if (fq == 0) { e[16 * t + fr] = Rr[t]; e[64 + 16 * t + fr] = Ri[t]; }
;             const float nr = fmaf(a64r[t], Rr[t], fmaf(-a64i[t], Ri[t], sr)), ni = fmaf(a64r[t], Ri[t], fmaf(a64i[t], Rr[t], si)); Rr[t] = nr; Ri[t] = ni;
;         }
;     }
.LBB0_674:
	global_store_dword v[116:117], v240, off offset:-256
	global_store_dword v[116:117], v241, off
	s_waitcnt vmcnt(9)
	v_mfma_f32_16x16x16_bf16 v[136:139], v[108:109], v[26:27], 0
	v_mfma_f32_16x16x16_bf16 v[140:143], v[108:109], v[28:29], 0
	s_waitcnt vmcnt(8)
	v_mfma_f32_16x16x16_bf16 v[136:139], v[112:113], v[30:31], v[136:139]
	v_mfma_f32_16x16x16_bf16 v[140:143], v[112:113], v[32:33], v[140:143]
	s_waitcnt vmcnt(7)
	v_mfma_f32_16x16x16_bf16 v[136:139], v[114:115], v[34:35], v[136:139]
	v_mfma_f32_16x16x16_bf16 v[140:143], v[114:115], v[36:37], v[140:143]
	s_waitcnt vmcnt(6)
	v_mfma_f32_16x16x16_bf16 v[136:139], v[110:111], v[38:39], v[136:139]
	v_mfma_f32_16x16x16_bf16 v[140:143], v[110:111], v[40:41], v[140:143]
	v_mfma_f32_16x16x16_bf16 v[196:199], v[108:109], v[48:49], 0
	v_mfma_f32_16x16x16_bf16 v[200:203], v[108:109], v[50:51], 0
	v_mfma_f32_16x16x16_bf16 v[196:199], v[112:113], v[52:53], v[196:199]
	v_mfma_f32_16x16x16_bf16 v[200:203], v[112:113], v[54:55], v[200:203]
	v_mfma_f32_16x16x16_bf16 v[196:199], v[114:115], v[56:57], v[196:199]
	v_mfma_f32_16x16x16_bf16 v[200:203], v[114:115], v[58:59], v[200:203]
	v_mfma_f32_16x16x16_bf16 v[196:199], v[110:111], v[60:61], v[196:199]
	v_mfma_f32_16x16x16_bf16 v[200:203], v[110:111], v[62:63], v[200:203]
	v_mfma_f32_16x16x16_bf16 v[208:211], v[108:109], v[70:71], 0
	v_mfma_f32_16x16x16_bf16 v[212:215], v[108:109], v[72:73], 0
	v_mfma_f32_16x16x16_bf16 v[208:211], v[112:113], v[74:75], v[208:211]
	v_mfma_f32_16x16x16_bf16 v[212:215], v[112:113], v[76:77], v[212:215]
	v_mfma_f32_16x16x16_bf16 v[208:211], v[114:115], v[78:79], v[208:211]
	v_mfma_f32_16x16x16_bf16 v[212:215], v[114:115], v[80:81], v[212:215]
	v_mfma_f32_16x16x16_bf16 v[208:211], v[110:111], v[82:83], v[208:211]
	v_mfma_f32_16x16x16_bf16 v[212:215], v[110:111], v[84:85], v[212:215]
	v_mfma_f32_16x16x16_bf16 v[224:227], v[108:109], v[88:89], 0
	v_mfma_f32_16x16x16_bf16 v[228:231], v[108:109], v[90:91], 0
	v_mfma_f32_16x16x16_bf16 v[224:227], v[112:113], v[96:97], v[224:227]
	v_mfma_f32_16x16x16_bf16 v[228:231], v[112:113], v[98:99], v[228:231]
	v_mfma_f32_16x16x16_bf16 v[224:227], v[114:115], v[100:101], v[224:227]
	v_mfma_f32_16x16x16_bf16 v[188:191], v[114:115], v[102:103], v[228:231]
	v_mfma_f32_16x16x16_bf16 v[224:227], v[110:111], v[104:105], v[224:227]
	v_mfma_f32_16x16x16_bf16 v[184:187], v[110:111], v[106:107], v[188:191]
	s_nop 6
	v_mov_b32_e32 v144, v136
	v_mov_b32_e32 v204, v196
	v_mov_b32_e32 v216, v208
	v_mov_b32_e32 v228, v224
	v_mov_b32_e32 v145, v140
	v_mov_b32_e32 v205, v200
	v_mov_b32_e32 v217, v212
	v_mov_b32_e32 v229, v184
	v_mov_b32_e32 v146, v137
	v_mov_b32_e32 v206, v197
	v_mov_b32_e32 v218, v209
	v_mov_b32_e32 v188, v225
	v_mov_b32_e32 v147, v141
	v_mov_b32_e32 v207, v201
	v_mov_b32_e32 v219, v213
	v_mov_b32_e32 v189, v185
	v_pk_fma_f32 v[144:145], v[18:19], v[144:145], v[146:147]
	v_pk_fma_f32 v[204:205], v[42:43], v[204:205], v[206:207]
	v_pk_fma_f32 v[216:217], v[64:65], v[216:217], v[218:219]
	v_pk_fma_f32 v[188:189], v[86:87], v[228:229], v[188:189]
	v_mov_b32_e32 v141, v136
	v_mov_b32_e32 v201, v196
	v_mov_b32_e32 v213, v208
	v_mov_b32_e32 v185, v224
	v_pk_fma_f32 v[136:137], v[0:1], v[140:141], v[144:145]
	v_pk_fma_f32 v[196:197], v[4:5], v[200:201], v[204:205]
	v_pk_fma_f32 v[208:209], v[8:9], v[212:213], v[216:217]
	v_pk_fma_f32 v[184:185], v[12:13], v[184:185], v[188:189]
	v_mov_b32_e32 v140, v138
	v_mov_b32_e32 v200, v198
	v_mov_b32_e32 v212, v210
	v_mov_b32_e32 v188, v226
	v_mov_b32_e32 v141, v142
	v_mov_b32_e32 v201, v202
	v_mov_b32_e32 v213, v214
	v_mov_b32_e32 v189, v186
	v_pk_fma_f32 v[140:141], v[18:19], v[136:137], v[140:141]
	v_pk_fma_f32 v[200:201], v[42:43], v[196:197], v[200:201]
	v_pk_fma_f32 v[212:213], v[64:65], v[208:209], v[212:213]
	v_pk_fma_f32 v[188:189], v[86:87], v[184:185], v[188:189]
	v_mov_b32_e32 v142, v139
	v_mov_b32_e32 v202, v199
	v_mov_b32_e32 v214, v211
	v_mov_b32_e32 v186, v227
	v_pk_fma_f32 v[136:137], v[0:1], v[136:137], v[140:141] op_sel:[0,1,0] op_sel_hi:[1,0,1]
	v_pk_fma_f32 v[196:197], v[4:5], v[196:197], v[200:201] op_sel:[0,1,0] op_sel_hi:[1,0,1]
	v_pk_fma_f32 v[208:209], v[8:9], v[208:209], v[212:213] op_sel:[0,1,0] op_sel_hi:[1,0,1]
	v_pk_fma_f32 v[184:185], v[12:13], v[184:185], v[188:189] op_sel:[0,1,0] op_sel_hi:[1,0,1]
	s_nop 0
	s_nop 0
	s_nop 0
	s_nop 0
	v_pk_fma_f32 v[138:139], v[18:19], v[136:137], v[142:143]
	v_pk_fma_f32 v[198:199], v[42:43], v[196:197], v[202:203]
	v_pk_fma_f32 v[210:211], v[64:65], v[208:209], v[214:215]
	v_pk_fma_f32 v[186:187], v[86:87], v[184:185], v[186:187]
	s_nop 0
	s_nop 0
	s_nop 0
	s_nop 0
	v_pk_fma_f32 v[136:137], v[0:1], v[136:137], v[138:139] op_sel:[0,1,0] op_sel_hi:[1,0,1]
	v_pk_fma_f32 v[196:197], v[4:5], v[196:197], v[198:199] op_sel:[0,1,0] op_sel_hi:[1,0,1]
	v_pk_fma_f32 v[208:209], v[8:9], v[208:209], v[210:211] op_sel:[0,1,0] op_sel_hi:[1,0,1]
	v_pk_fma_f32 v[184:185], v[12:13], v[184:185], v[186:187] op_sel:[0,1,0] op_sel_hi:[1,0,1]
	s_nop 0
	s_nop 0
	s_nop 0
	s_nop 0
	v_pk_fma_f32 v[138:139], v[22:23], v[136:137], 0 op_sel_hi:[1,1,0]
	v_pk_fma_f32 v[198:199], v[44:45], v[196:197], 0 op_sel_hi:[1,1,0]
	v_pk_fma_f32 v[210:211], v[66:67], v[208:209], 0 op_sel_hi:[1,1,0]
	v_pk_fma_f32 v[186:187], v[92:93], v[184:185], 0 op_sel_hi:[1,1,0]
	s_nop 0
	s_nop 0
	s_nop 0
	s_nop 0
	v_pk_fma_f32 v[136:137], v[24:25], v[136:137], v[138:139] op_sel:[0,1,0] op_sel_hi:[1,0,1]
	v_pk_fma_f32 v[196:197], v[46:47], v[196:197], v[198:199] op_sel:[0,1,0] op_sel_hi:[1,0,1]
	v_pk_fma_f32 v[208:209], v[68:69], v[208:209], v[210:211] op_sel:[0,1,0] op_sel_hi:[1,0,1]
	v_pk_fma_f32 v[184:185], v[94:95], v[184:185], v[186:187] op_sel:[0,1,0] op_sel_hi:[1,0,1]
	s_nop 1
	v_permlane32_swap_b32_e32 v136, v208
	v_permlane32_swap_b32_e32 v137, v209
	v_permlane32_swap_b32_e32 v196, v184
	v_permlane32_swap_b32_e32 v197, v185
	v_add_f32_e32 v136, v136, v208
	v_add_f32_e32 v196, v196, v184
	v_add_f32_e32 v137, v137, v209
	v_add_f32_e32 v197, v197, v185
	s_nop 0
	v_permlane16_swap_b32_e32 v136, v196
	v_permlane16_swap_b32_e32 v137, v197
	v_add_f32_e32 v136, v136, v196
	v_add_f32_e32 v137, v137, v197
	v_fma_f32 v244, -v243, v241, v136
	v_fma_f32 v245, v243, v240, v137
	v_fma_f32 v240, v242, v240, v244
	v_fma_f32 v241, v242, v241, v245
	v_lshl_add_u64 v[116:117], v[116:117], 0, s[4:5]
	v_add_u32_e32 v20, 64, v20
	s_and_b64 vcc, exec, s[22:23]
	s_cbranch_vccnz .LBB0_702
	s_mov_b32 s24, s40
	s_waitcnt vmcnt(3)
	v_mov_b32_e32 v108, v118
	v_mov_b32_e32 v109, v119
	s_waitcnt vmcnt(2)
	v_mov_b32_e32 v112, v120
	v_mov_b32_e32 v113, v121
	s_waitcnt vmcnt(1)
	v_mov_b32_e32 v114, v122
	v_mov_b32_e32 v115, v123
	s_waitcnt vmcnt(0)
	v_mov_b32_e32 v110, v124
	v_mov_b32_e32 v111, v125
	s_branch .LBB0_671

; template <int DIR>
; __device__ __forceinline__ void s5_local_dir(const bf16_t* UZ, unsigned char* ws, int gw, int NGW, int lane) {
;     ...
;     float* fin = q < 3 ? (float*)(ws + WS_QE) + ((size_t)((b * 2 + DIR) * 64 + g) * 3 + q) * 128 : ebase + (size_t)67 * 128;
;     if (fq == 0) {
; #pragma unroll
;         for (int t = 0; t < 4; ++t) { fin[16 * t + fr] = Rr[t]; fin[64 + 16 * t + fr] = Ri[t]; }
;     }
.LBB0_686:
.LBB0_687:
	s_mov_b64 s[4:5], exec
	s_cmp_eq_u64 s[8:9], 0
	s_cbranch_scc1 .LBB0_689
.LBB0_688:
	s_waitcnt vmcnt(0)
	v_lshlrev_b32_e32 v0, 2, v126
	global_store_dword v0, v240, s[2:3]
	global_store_dword v0, v241, s[2:3] offset:256

; template <int DIR>
; __device__ __forceinline__ void s5_local_dir(const bf16_t* UZ, unsigned char* ws, int gw, int NGW, int lane) {
;     ...
;     float* fin = q < 3 ? (float*)(ws + WS_QE) + ((size_t)((b * 2 + DIR) * 64 + g) * 3 + q) * 128 : ebase + (size_t)67 * 128;
;     if (fq == 0) {
; #pragma unroll
;         for (int t = 0; t < 4; ++t) { fin[16 * t + fr] = Rr[t]; fin[64 + 16 * t + fr] = Ri[t]; }
;     }
.LBB0_725:
	s_mov_b64 s[4:5], exec
	s_branch .LBB0_688
